# nt hint also on the merge-epilogue gate loads and the down-epilogue bf16 residual loads (once-read streams)
# baseline (speedup 1.0000x reference)
; __device__ __forceinline__ unsigned cvt_pk_bf16(float lo, float hi) { unsigned r; asm volatile("v_cvt_pk_bf16_f32 %0, %1, %2" : "=v"(r) : "v"(lo), "v"(hi)); return r; }
; __device__ __forceinline__ float bf_lo(unsigned w) { return __uint_as_float(w << 16); }
; __device__ __forceinline__ float bf_hi(unsigned w) { return __uint_as_float(w & 0xffff0000u); }
;     __device__ __forceinline__ void operator()(const f32x4 (&acc)[2][2][4][2], const Unit& u, int wr, int wc, int fr, int fq) const {
;         const int row0 = u.pm * BM + wr * 64 + fr, col0 = u.pn * BM + wc * 32 + 8 * fq;
; #pragma unroll
;         for (int ai = 0; ai < 2; ++ai)
; #pragma unroll
;             for (int m = 0; m < 4; ++m) { const size_t row = (size_t)(row0 + ai * HALF + m * 16);
; #pragma unroll
;                 for (int bj = 0; bj < 2; ++bj) { const f32x4 v0 = acc[ai][bj][m][0], v1 = acc[ai][bj][m][1];
;                     const u32x2 g = *(const u32x2*)(G + row * ldg + col0 + bj * HALF);
;                     float o[8]; const float k255 = 1.0f / 255.0f;
;                     o[0] = v0[0] * ((float)(g.x & 0xffu) * k255); o[1] = v0[1] * ((float)((g.x >> 8) & 0xffu) * k255); o[2] = v0[2] * ((float)((g.x >> 16) & 0xffu) * k255); o[3] = v0[3] * ((float)(g.x >> 24) * k255);
;                     o[4] = v1[0] * ((float)(g.y & 0xffu) * k255); o[5] = v1[1] * ((float)((g.y >> 8) & 0xffu) * k255); o[6] = v1[2] * ((float)((g.y >> 16) & 0xffu) * k255); o[7] = v1[3] * ((float)(g.y >> 24) * k255);
;                     bf16_t* dst = MG + row * 1024 + col0 + bj * HALF;
;                     if (SECOND) { const u32x4 p = *(const u32x4*)dst;
;                         o[0] += bf_lo(p.x); o[1] += bf_hi(p.x); o[2] += bf_lo(p.y); o[3] += bf_hi(p.y); o[4] += bf_lo(p.z); o[5] += bf_hi(p.z); o[6] += bf_lo(p.w); o[7] += bf_hi(p.w); }
;                     u32x4 w; w.x = cvt_pk_bf16(o[0], o[1]); w.y = cvt_pk_bf16(o[2], o[3]); w.z = cvt_pk_bf16(o[4], o[5]); w.w = cvt_pk_bf16(o[6], o[7]);
;                     *(u32x4*)dst = w; } }
.LBB0_687:
	v_lshl_add_u32 v150, s40, 8, v1
	v_ashrrev_i32_e32 v151, 31, v150
	v_lshl_or_b32 v146, s23, 8, v153
	v_lshlrev_b64 v[148:149], 11, v[150:151]
	v_ashrrev_i32_e32 v147, 31, v146
	v_lshl_add_u64 v[156:157], s[14:15], 0, v[148:149]
	v_lshl_add_u64 v[156:157], v[156:157], 0, v[146:147]
	s_mov_b32 s77, 0
	v_mov_b32_e32 v252, v156
	v_mov_b32_e32 v253, v157
	global_load_dwordx2 v[200:201], v[252:253], off nt
	global_load_dwordx2 v[202:203], v[252:253], off offset:128 nt
	s_mov_b32 s76, 0x8000
	v_lshl_add_u64 v[250:251], v[252:253], 0, s[76:77]
	global_load_dwordx2 v[204:205], v[250:251], off nt
	global_load_dwordx2 v[206:207], v[250:251], off offset:128 nt
	s_mov_b32 s76, 0x10000
	v_lshl_add_u64 v[250:251], v[252:253], 0, s[76:77]
	global_load_dwordx2 v[208:209], v[250:251], off nt
	global_load_dwordx2 v[210:211], v[250:251], off offset:128 nt
	s_mov_b32 s76, 0x18000
	v_lshl_add_u64 v[250:251], v[252:253], 0, s[76:77]
	global_load_dwordx2 v[212:213], v[250:251], off nt
	global_load_dwordx2 v[214:215], v[250:251], off offset:128 nt
	s_mov_b32 s76, 0x40000
	v_lshl_add_u64 v[250:251], v[252:253], 0, s[76:77]
	global_load_dwordx2 v[216:217], v[250:251], off nt
	global_load_dwordx2 v[218:219], v[250:251], off offset:128 nt
	s_mov_b32 s76, 0x48000
	v_lshl_add_u64 v[250:251], v[252:253], 0, s[76:77]
	global_load_dwordx2 v[220:221], v[250:251], off nt
	global_load_dwordx2 v[222:223], v[250:251], off offset:128 nt
	s_mov_b64 s[20:21], 0x48000
	s_and_b64 vcc, exec, s[4:5]
	s_waitcnt vmcnt(11)
	s_nop 1
	v_mov_b32_e32 v158, v200
	v_mov_b32_e32 v159, v201
	v_cvt_f32_ubyte0_e32 v151, v158
	v_mul_f32_e32 v151, 0x3b808081, v151
	v_mul_f32_e32 v130, v130, v151
	v_cvt_f32_ubyte1_e32 v151, v158
	v_mul_f32_e32 v151, 0x3b808081, v151
	v_mul_f32_e32 v131, v131, v151
	v_cvt_f32_ubyte2_e32 v151, v158
	v_mul_f32_e32 v151, 0x3b808081, v151
	v_mul_f32_e32 v151, v132, v151
	v_cvt_f32_ubyte3_e32 v132, v158
	v_mul_f32_e32 v132, 0x3b808081, v132
	v_mul_f32_e32 v155, v133, v132
	v_cvt_f32_ubyte0_e32 v132, v159
	v_mul_f32_e32 v132, 0x3b808081, v132
	v_mul_f32_e32 v158, v126, v132
	v_cvt_f32_ubyte1_e32 v126, v159
	v_mul_f32_e32 v126, 0x3b808081, v126
	v_mul_f32_e32 v160, v127, v126
	v_cvt_f32_ubyte2_e32 v126, v159
	v_mul_f32_e32 v126, 0x3b808081, v126
	v_mul_f32_e32 v161, v128, v126
	v_cvt_f32_ubyte3_e32 v126, v159
	v_mul_f32_e32 v126, 0x3b808081, v126
	v_mul_f32_e32 v159, v129, v126
	v_lshl_add_u64 v[128:129], s[12:13], 0, v[148:149]
	v_lshlrev_b64 v[126:127], 1, v[146:147]
	v_lshl_add_u64 v[132:133], v[128:129], 0, v[126:127]
	v_cvt_pk_bf16_f32 v128, v130, v131
	v_cvt_pk_bf16_f32 v129, v151, v155
	v_cvt_pk_bf16_f32 v130, v158, v160
	v_cvt_pk_bf16_f32 v131, v161, v159
	global_store_dwordx4 v[132:133], v[128:131], off
	s_waitcnt vmcnt(11)
	s_nop 1
	v_mov_b32_e32 v128, v202
	v_mov_b32_e32 v129, v203
	s_mov_b32 s76, 0x50000
	v_lshl_add_u64 v[250:251], v[252:253], 0, s[76:77]
	global_load_dwordx2 v[200:201], v[250:251], off nt
	global_load_dwordx2 v[202:203], v[250:251], off offset:128 nt
	v_cvt_f32_ubyte0_e32 v130, v128
	v_mul_f32_e32 v130, 0x3b808081, v130
	v_mul_f32_e32 v122, v122, v130
	v_cvt_f32_ubyte1_e32 v130, v128
	v_mul_f32_e32 v130, 0x3b808081, v130
	v_mul_f32_e32 v123, v123, v130
	v_cvt_f32_ubyte2_e32 v130, v128
	v_cvt_f32_ubyte3_e32 v128, v128
	v_mul_f32_e32 v128, 0x3b808081, v128
	v_mul_f32_e32 v125, v125, v128
	v_cvt_f32_ubyte0_e32 v128, v129
	v_mul_f32_e32 v128, 0x3b808081, v128
	v_mul_f32_e32 v128, v118, v128
	v_cvt_f32_ubyte1_e32 v118, v129
	v_mul_f32_e32 v130, 0x3b808081, v130
	v_mul_f32_e32 v118, 0x3b808081, v118
	v_mul_f32_e32 v124, v124, v130
	v_mul_f32_e32 v130, v119, v118
	v_cvt_f32_ubyte2_e32 v118, v129
	v_mul_f32_e32 v118, 0x3b808081, v118
	v_mul_f32_e32 v131, v120, v118
	v_cvt_f32_ubyte3_e32 v118, v129
	v_mul_f32_e32 v118, 0x3b808081, v118
	v_mul_f32_e32 v121, v121, v118
	v_cvt_pk_bf16_f32 v118, v122, v123
	v_cvt_pk_bf16_f32 v119, v124, v125
	v_cvt_pk_bf16_f32 v120, v128, v130
	v_cvt_pk_bf16_f32 v121, v131, v121
	global_store_dwordx4 v[132:133], v[118:121], off offset:256
	s_nop 1
	v_or_b32_e32 v118, 16, v150
	v_ashrrev_i32_e32 v119, 31, v118
	v_lshlrev_b64 v[120:121], 11, v[118:119]
	v_lshl_add_u64 v[118:119], s[14:15], 0, v[120:121]
	v_lshl_add_u64 v[118:119], v[118:119], 0, v[146:147]
	s_waitcnt vmcnt(13)
	s_nop 1
	v_mov_b32_e32 v122, v204
	v_mov_b32_e32 v123, v205
	v_cvt_f32_ubyte0_e32 v124, v122
	v_mul_f32_e32 v124, 0x3b808081, v124
	v_mul_f32_e32 v124, v114, v124
	v_cvt_f32_ubyte1_e32 v114, v122
	v_mul_f32_e32 v114, 0x3b808081, v114
	v_mul_f32_e32 v125, v115, v114
	v_cvt_f32_ubyte2_e32 v114, v122
	v_mul_f32_e32 v114, 0x3b808081, v114
	v_mul_f32_e32 v116, v116, v114
	v_cvt_f32_ubyte3_e32 v114, v122
	v_mul_f32_e32 v114, 0x3b808081, v114
	v_mul_f32_e32 v117, v117, v114
	v_cvt_f32_ubyte0_e32 v114, v123
	v_mul_f32_e32 v114, 0x3b808081, v114
	v_mul_f32_e32 v122, v110, v114
	v_cvt_f32_ubyte1_e32 v110, v123
	v_mul_f32_e32 v110, 0x3b808081, v110
	v_mul_f32_e32 v128, v111, v110
	v_cvt_f32_ubyte2_e32 v110, v123
	v_mul_f32_e32 v110, 0x3b808081, v110
	v_mul_f32_e32 v129, v112, v110
	v_cvt_f32_ubyte3_e32 v110, v123
	v_mul_f32_e32 v110, 0x3b808081, v110
	v_mul_f32_e32 v113, v113, v110
	v_lshl_add_u64 v[110:111], s[12:13], 0, v[120:121]
	v_lshl_add_u64 v[114:115], v[110:111], 0, v[126:127]
	v_cvt_pk_bf16_f32 v110, v124, v125
	v_cvt_pk_bf16_f32 v111, v116, v117
	v_cvt_pk_bf16_f32 v112, v122, v128
	v_cvt_pk_bf16_f32 v113, v129, v113
	global_store_dwordx4 v[114:115], v[110:113], off
	s_waitcnt vmcnt(13)
; __device__ __forceinline__ unsigned cvt_pk_bf16(float lo, float hi) { unsigned r; asm volatile("v_cvt_pk_bf16_f32 %0, %1, %2" : "=v"(r) : "v"(lo), "v"(hi)); return r; }
; __device__ __forceinline__ float bf_lo(unsigned w) { return __uint_as_float(w << 16); }
; __device__ __forceinline__ float bf_hi(unsigned w) { return __uint_as_float(w & 0xffff0000u); }
;     __device__ __forceinline__ void operator()(const f32x4 (&acc)[2][2][4][2], const Unit& u, int wr, int wc, int fr, int fq) const {
;         const int row0 = u.pm * BM + wr * 64 + fr, col0 = u.pn * BM + wc * 32 + 8 * fq;
; #pragma unroll
;         for (int ai = 0; ai < 2; ++ai)
; #pragma unroll
;             for (int m = 0; m < 4; ++m) { const size_t row = (size_t)(row0 + ai * HALF + m * 16);
; #pragma unroll
;                 for (int bj = 0; bj < 2; ++bj) { const f32x4 v0 = acc[ai][bj][m][0], v1 = acc[ai][bj][m][1];
;                     const u32x2 g = *(const u32x2*)(G + row * ldg + col0 + bj * HALF);
;                     float o[8]; const float k255 = 1.0f / 255.0f;
;                     o[0] = v0[0] * ((float)(g.x & 0xffu) * k255); o[1] = v0[1] * ((float)((g.x >> 8) & 0xffu) * k255); o[2] = v0[2] * ((float)((g.x >> 16) & 0xffu) * k255); o[3] = v0[3] * ((float)(g.x >> 24) * k255);
;                     o[4] = v1[0] * ((float)(g.y & 0xffu) * k255); o[5] = v1[1] * ((float)((g.y >> 8) & 0xffu) * k255); o[6] = v1[2] * ((float)((g.y >> 16) & 0xffu) * k255); o[7] = v1[3] * ((float)(g.y >> 24) * k255);
;                     bf16_t* dst = MG + row * 1024 + col0 + bj * HALF;
;                     if (SECOND) { const u32x4 p = *(const u32x4*)dst;
;                         o[0] += bf_lo(p.x); o[1] += bf_hi(p.x); o[2] += bf_lo(p.y); o[3] += bf_hi(p.y); o[4] += bf_lo(p.z); o[5] += bf_hi(p.z); o[6] += bf_lo(p.w); o[7] += bf_hi(p.w); }
;                     u32x4 w; w.x = cvt_pk_bf16(o[0], o[1]); w.y = cvt_pk_bf16(o[2], o[3]); w.z = cvt_pk_bf16(o[4], o[5]); w.w = cvt_pk_bf16(o[6], o[7]);
;                     *(u32x4*)dst = w; } }
	s_nop 1
	v_mov_b32_e32 v110, v206
	v_mov_b32_e32 v111, v207
	s_mov_b32 s76, 0x58000
	v_lshl_add_u64 v[250:251], v[252:253], 0, s[76:77]
	global_load_dwordx2 v[204:205], v[250:251], off nt
	global_load_dwordx2 v[206:207], v[250:251], off offset:128 nt
	v_cvt_f32_ubyte0_e32 v112, v110
	v_mul_f32_e32 v112, 0x3b808081, v112
	v_mul_f32_e32 v106, v106, v112
	v_cvt_f32_ubyte1_e32 v112, v110
	v_mul_f32_e32 v112, 0x3b808081, v112
	v_mul_f32_e32 v107, v107, v112
	v_cvt_f32_ubyte2_e32 v112, v110
	v_cvt_f32_ubyte3_e32 v110, v110
	v_mul_f32_e32 v110, 0x3b808081, v110
	v_mul_f32_e32 v109, v109, v110
	v_cvt_f32_ubyte0_e32 v110, v111
	v_mul_f32_e32 v110, 0x3b808081, v110
	v_mul_f32_e32 v110, v102, v110
	v_cvt_f32_ubyte1_e32 v102, v111
	v_mul_f32_e32 v112, 0x3b808081, v112
	v_mul_f32_e32 v102, 0x3b808081, v102
	v_mul_f32_e32 v108, v108, v112
	v_mul_f32_e32 v112, v103, v102
	v_cvt_f32_ubyte2_e32 v102, v111
	v_mul_f32_e32 v102, 0x3b808081, v102
	v_mul_f32_e32 v113, v104, v102
	v_cvt_f32_ubyte3_e32 v102, v111
	v_mul_f32_e32 v102, 0x3b808081, v102
	v_mul_f32_e32 v105, v105, v102
	v_cvt_pk_bf16_f32 v102, v106, v107
	v_cvt_pk_bf16_f32 v103, v108, v109
	v_cvt_pk_bf16_f32 v104, v110, v112
	v_cvt_pk_bf16_f32 v105, v113, v105
	global_store_dwordx4 v[114:115], v[102:105], off offset:256
	s_nop 1
	v_or_b32_e32 v102, 32, v150
	v_ashrrev_i32_e32 v103, 31, v102
	v_lshlrev_b64 v[104:105], 11, v[102:103]
	v_lshl_add_u64 v[102:103], s[14:15], 0, v[104:105]
	v_lshl_add_u64 v[102:103], v[102:103], 0, v[146:147]
	s_waitcnt vmcnt(15)
	s_nop 1
	v_mov_b32_e32 v106, v208
	v_mov_b32_e32 v107, v209
	v_cvt_f32_ubyte0_e32 v108, v106
	v_mul_f32_e32 v108, 0x3b808081, v108
	v_mul_f32_e32 v108, v98, v108
	v_cvt_f32_ubyte1_e32 v98, v106
	v_mul_f32_e32 v98, 0x3b808081, v98
	v_mul_f32_e32 v109, v99, v98
	v_cvt_f32_ubyte2_e32 v98, v106
	v_mul_f32_e32 v98, 0x3b808081, v98
	v_mul_f32_e32 v100, v100, v98
	v_cvt_f32_ubyte3_e32 v98, v106
	v_mul_f32_e32 v98, 0x3b808081, v98
	v_mul_f32_e32 v101, v101, v98
	v_cvt_f32_ubyte0_e32 v98, v107
	v_mul_f32_e32 v98, 0x3b808081, v98
	v_mul_f32_e32 v106, v94, v98
	v_cvt_f32_ubyte1_e32 v94, v107
	v_mul_f32_e32 v94, 0x3b808081, v94
	v_mul_f32_e32 v110, v95, v94
	v_cvt_f32_ubyte2_e32 v94, v107
	v_mul_f32_e32 v94, 0x3b808081, v94
	v_mul_f32_e32 v111, v96, v94
	v_cvt_f32_ubyte3_e32 v94, v107
	v_mul_f32_e32 v94, 0x3b808081, v94
	v_mul_f32_e32 v97, v97, v94
	v_lshl_add_u64 v[94:95], s[12:13], 0, v[104:105]
	v_lshl_add_u64 v[98:99], v[94:95], 0, v[126:127]
	v_cvt_pk_bf16_f32 v94, v108, v109
	v_cvt_pk_bf16_f32 v95, v100, v101
	v_cvt_pk_bf16_f32 v96, v106, v110
	v_cvt_pk_bf16_f32 v97, v111, v97
	global_store_dwordx4 v[98:99], v[94:97], off
	s_waitcnt vmcnt(15)
	s_nop 1
	v_mov_b32_e32 v94, v210
	v_mov_b32_e32 v95, v211
	v_cvt_f32_ubyte0_e32 v96, v94
	v_mul_f32_e32 v96, 0x3b808081, v96
	v_mul_f32_e32 v90, v90, v96
	v_cvt_f32_ubyte1_e32 v96, v94
	v_mul_f32_e32 v96, 0x3b808081, v96
	v_mul_f32_e32 v91, v91, v96
	v_cvt_f32_ubyte2_e32 v96, v94
	v_cvt_f32_ubyte3_e32 v94, v94
	v_mul_f32_e32 v94, 0x3b808081, v94
	v_mul_f32_e32 v93, v93, v94
	v_cvt_f32_ubyte0_e32 v94, v95
	v_mul_f32_e32 v94, 0x3b808081, v94
	v_mul_f32_e32 v94, v86, v94
	v_cvt_f32_ubyte1_e32 v86, v95
	v_mul_f32_e32 v96, 0x3b808081, v96
	v_mul_f32_e32 v86, 0x3b808081, v86
	v_mul_f32_e32 v92, v92, v96
	v_mul_f32_e32 v96, v87, v86
	v_cvt_f32_ubyte2_e32 v86, v95
	v_mul_f32_e32 v86, 0x3b808081, v86
	v_mul_f32_e32 v97, v88, v86
	v_cvt_f32_ubyte3_e32 v86, v95
	v_mul_f32_e32 v86, 0x3b808081, v86
	v_mul_f32_e32 v89, v89, v86
	v_cvt_pk_bf16_f32 v86, v90, v91
	v_cvt_pk_bf16_f32 v87, v92, v93
	v_cvt_pk_bf16_f32 v88, v94, v96
	v_cvt_pk_bf16_f32 v89, v97, v89
	global_store_dwordx4 v[98:99], v[86:89], off offset:256
	s_nop 1
	v_or_b32_e32 v86, 48, v150
	v_ashrrev_i32_e32 v87, 31, v86
	v_lshlrev_b64 v[88:89], 11, v[86:87]
	v_lshl_add_u64 v[86:87], s[14:15], 0, v[88:89]
	v_lshl_add_u64 v[86:87], v[86:87], 0, v[146:147]
	s_waitcnt vmcnt(15)
	s_nop 1
	v_mov_b32_e32 v90, v212
	v_mov_b32_e32 v91, v213
	v_cvt_f32_ubyte0_e32 v92, v90
	v_mul_f32_e32 v92, 0x3b808081, v92
	v_mul_f32_e32 v92, v78, v92
	v_cvt_f32_ubyte1_e32 v78, v90
	v_mul_f32_e32 v78, 0x3b808081, v78
	v_mul_f32_e32 v93, v79, v78
	v_cvt_f32_ubyte2_e32 v78, v90
	v_mul_f32_e32 v78, 0x3b808081, v78
	v_mul_f32_e32 v80, v80, v78
	v_cvt_f32_ubyte3_e32 v78, v90
	v_mul_f32_e32 v78, 0x3b808081, v78
	v_mul_f32_e32 v81, v81, v78
	v_cvt_f32_ubyte0_e32 v78, v91
	v_mul_f32_e32 v78, 0x3b808081, v78
	v_mul_f32_e32 v90, v74, v78
	v_cvt_f32_ubyte1_e32 v74, v91
	v_mul_f32_e32 v74, 0x3b808081, v74
	v_mul_f32_e32 v94, v75, v74
	v_cvt_f32_ubyte2_e32 v74, v91
	v_mul_f32_e32 v74, 0x3b808081, v74
	v_mul_f32_e32 v95, v76, v74
	v_cvt_f32_ubyte3_e32 v74, v91
	v_mul_f32_e32 v74, 0x3b808081, v74
	v_mul_f32_e32 v77, v77, v74
	v_lshl_add_u64 v[74:75], s[12:13], 0, v[88:89]
	v_lshl_add_u64 v[78:79], v[74:75], 0, v[126:127]
	v_cvt_pk_bf16_f32 v74, v92, v93
	v_cvt_pk_bf16_f32 v75, v80, v81
	v_cvt_pk_bf16_f32 v76, v90, v94
	v_cvt_pk_bf16_f32 v77, v95, v77
	global_store_dwordx4 v[78:79], v[74:77], off
	s_waitcnt vmcnt(15)
; __device__ __forceinline__ unsigned cvt_pk_bf16(float lo, float hi) { unsigned r; asm volatile("v_cvt_pk_bf16_f32 %0, %1, %2" : "=v"(r) : "v"(lo), "v"(hi)); return r; }
; __device__ __forceinline__ float bf_lo(unsigned w) { return __uint_as_float(w << 16); }
; __device__ __forceinline__ float bf_hi(unsigned w) { return __uint_as_float(w & 0xffff0000u); }
;     __device__ __forceinline__ void operator()(const f32x4 (&acc)[2][2][4][2], const Unit& u, int wr, int wc, int fr, int fq) const {
;         const int row0 = u.pm * BM + wr * 64 + fr, col0 = u.pn * BM + wc * 32 + 8 * fq;
; #pragma unroll
;         for (int ai = 0; ai < 2; ++ai)
; #pragma unroll
;             for (int m = 0; m < 4; ++m) { const size_t row = (size_t)(row0 + ai * HALF + m * 16);
; #pragma unroll
;                 for (int bj = 0; bj < 2; ++bj) { const f32x4 v0 = acc[ai][bj][m][0], v1 = acc[ai][bj][m][1];
;                     const u32x2 g = *(const u32x2*)(G + row * ldg + col0 + bj * HALF);
;                     float o[8]; const float k255 = 1.0f / 255.0f;
;                     o[0] = v0[0] * ((float)(g.x & 0xffu) * k255); o[1] = v0[1] * ((float)((g.x >> 8) & 0xffu) * k255); o[2] = v0[2] * ((float)((g.x >> 16) & 0xffu) * k255); o[3] = v0[3] * ((float)(g.x >> 24) * k255);
;                     o[4] = v1[0] * ((float)(g.y & 0xffu) * k255); o[5] = v1[1] * ((float)((g.y >> 8) & 0xffu) * k255); o[6] = v1[2] * ((float)((g.y >> 16) & 0xffu) * k255); o[7] = v1[3] * ((float)(g.y >> 24) * k255);
;                     bf16_t* dst = MG + row * 1024 + col0 + bj * HALF;
;                     if (SECOND) { const u32x4 p = *(const u32x4*)dst;
;                         o[0] += bf_lo(p.x); o[1] += bf_hi(p.x); o[2] += bf_lo(p.y); o[3] += bf_hi(p.y); o[4] += bf_lo(p.z); o[5] += bf_hi(p.z); o[6] += bf_lo(p.w); o[7] += bf_hi(p.w); }
;                     u32x4 w; w.x = cvt_pk_bf16(o[0], o[1]); w.y = cvt_pk_bf16(o[2], o[3]); w.z = cvt_pk_bf16(o[4], o[5]); w.w = cvt_pk_bf16(o[6], o[7]);
;                     *(u32x4*)dst = w; } }
	s_nop 1
	v_mov_b32_e32 v74, v214
	v_mov_b32_e32 v75, v215
	v_cvt_f32_ubyte0_e32 v76, v74
	v_mul_f32_e32 v76, 0x3b808081, v76
	v_mul_f32_e32 v70, v70, v76
	v_cvt_f32_ubyte1_e32 v76, v74
	v_mul_f32_e32 v76, 0x3b808081, v76
	v_mul_f32_e32 v71, v71, v76
	v_cvt_f32_ubyte2_e32 v76, v74
	v_cvt_f32_ubyte3_e32 v74, v74
	v_mul_f32_e32 v74, 0x3b808081, v74
	v_mul_f32_e32 v73, v73, v74
	v_cvt_f32_ubyte0_e32 v74, v75
	v_mul_f32_e32 v74, 0x3b808081, v74
	v_mul_f32_e32 v74, v66, v74
	v_cvt_f32_ubyte1_e32 v66, v75
	v_mul_f32_e32 v76, 0x3b808081, v76
	v_mul_f32_e32 v66, 0x3b808081, v66
	v_mul_f32_e32 v72, v72, v76
	v_mul_f32_e32 v76, v67, v66
	v_cvt_f32_ubyte2_e32 v66, v75
	v_mul_f32_e32 v66, 0x3b808081, v66
	v_mul_f32_e32 v77, v68, v66
	v_cvt_f32_ubyte3_e32 v66, v75
	v_mul_f32_e32 v66, 0x3b808081, v66
	v_mul_f32_e32 v69, v69, v66
	v_cvt_pk_bf16_f32 v66, v70, v71
	v_cvt_pk_bf16_f32 v67, v72, v73
	v_cvt_pk_bf16_f32 v68, v74, v76
	v_cvt_pk_bf16_f32 v69, v77, v69
	global_store_dwordx4 v[78:79], v[66:69], off offset:256
	s_nop 1
	v_lshl_add_u64 v[68:69], v[148:149], 0, s[68:69]
	v_lshl_add_u64 v[66:67], s[14:15], 0, v[68:69]
	v_lshl_add_u64 v[66:67], v[66:67], 0, v[146:147]
	s_waitcnt vmcnt(15)
	s_nop 1
	v_mov_b32_e32 v70, v216
	v_mov_b32_e32 v71, v217
	v_cvt_f32_ubyte0_e32 v72, v70
	v_mul_f32_e32 v72, 0x3b808081, v72
	v_mul_f32_e32 v72, v62, v72
	v_cvt_f32_ubyte1_e32 v62, v70
	v_mul_f32_e32 v62, 0x3b808081, v62
	v_mul_f32_e32 v73, v63, v62
	v_cvt_f32_ubyte2_e32 v62, v70
	v_mul_f32_e32 v62, 0x3b808081, v62
	v_mul_f32_e32 v64, v64, v62
	v_cvt_f32_ubyte3_e32 v62, v70
	v_mul_f32_e32 v62, 0x3b808081, v62
	v_mul_f32_e32 v65, v65, v62
	v_cvt_f32_ubyte0_e32 v62, v71
	v_mul_f32_e32 v62, 0x3b808081, v62
	v_mul_f32_e32 v70, v58, v62
	v_cvt_f32_ubyte1_e32 v58, v71
	v_mul_f32_e32 v58, 0x3b808081, v58
	v_mul_f32_e32 v74, v59, v58
	v_cvt_f32_ubyte2_e32 v58, v71
	v_mul_f32_e32 v58, 0x3b808081, v58
	v_mul_f32_e32 v75, v60, v58
	v_cvt_f32_ubyte3_e32 v58, v71
	v_mul_f32_e32 v58, 0x3b808081, v58
	v_mul_f32_e32 v61, v61, v58
	v_lshl_add_u64 v[58:59], s[12:13], 0, v[68:69]
	v_lshl_add_u64 v[62:63], v[58:59], 0, v[126:127]
	v_cvt_pk_bf16_f32 v58, v72, v73
	v_cvt_pk_bf16_f32 v59, v64, v65
	v_cvt_pk_bf16_f32 v60, v70, v74
	v_cvt_pk_bf16_f32 v61, v75, v61
	global_store_dwordx4 v[62:63], v[58:61], off
	s_waitcnt vmcnt(15)
	s_nop 1
	v_mov_b32_e32 v58, v218
	v_mov_b32_e32 v59, v219
	v_cvt_f32_ubyte0_e32 v60, v58
	v_mul_f32_e32 v60, 0x3b808081, v60
	v_mul_f32_e32 v54, v54, v60
	v_cvt_f32_ubyte1_e32 v60, v58
	v_mul_f32_e32 v60, 0x3b808081, v60
	v_mul_f32_e32 v55, v55, v60
	v_cvt_f32_ubyte2_e32 v60, v58
	v_cvt_f32_ubyte3_e32 v58, v58
	v_mul_f32_e32 v58, 0x3b808081, v58
	v_mul_f32_e32 v57, v57, v58
	v_cvt_f32_ubyte0_e32 v58, v59
	v_mul_f32_e32 v58, 0x3b808081, v58
	v_mul_f32_e32 v58, v50, v58
	v_cvt_f32_ubyte1_e32 v50, v59
	v_mul_f32_e32 v60, 0x3b808081, v60
	v_mul_f32_e32 v50, 0x3b808081, v50
	v_mul_f32_e32 v56, v56, v60
	v_mul_f32_e32 v60, v51, v50
	v_cvt_f32_ubyte2_e32 v50, v59
	v_mul_f32_e32 v50, 0x3b808081, v50
	v_mul_f32_e32 v61, v52, v50
	v_cvt_f32_ubyte3_e32 v50, v59
	v_mul_f32_e32 v50, 0x3b808081, v50
	v_mul_f32_e32 v53, v53, v50
	v_cvt_pk_bf16_f32 v50, v54, v55
	v_cvt_pk_bf16_f32 v51, v56, v57
	v_cvt_pk_bf16_f32 v52, v58, v60
	v_cvt_pk_bf16_f32 v53, v61, v53
	global_store_dwordx4 v[62:63], v[50:53], off offset:256
	s_nop 1
	v_lshl_add_u64 v[52:53], v[148:149], 0, s[20:21]
	v_lshl_add_u64 v[50:51], s[14:15], 0, v[52:53]
	v_lshl_add_u64 v[50:51], v[50:51], 0, v[146:147]
	s_mov_b64 s[20:21], 0x50000
	s_waitcnt vmcnt(15)
	s_nop 1
	v_mov_b32_e32 v54, v220
	v_mov_b32_e32 v55, v221
	v_cvt_f32_ubyte0_e32 v56, v54
	v_mul_f32_e32 v56, 0x3b808081, v56
	v_mul_f32_e32 v56, v46, v56
	v_cvt_f32_ubyte1_e32 v46, v54
	v_mul_f32_e32 v46, 0x3b808081, v46
	v_mul_f32_e32 v57, v47, v46
	v_cvt_f32_ubyte2_e32 v46, v54
	v_mul_f32_e32 v46, 0x3b808081, v46
	v_mul_f32_e32 v48, v48, v46
	v_cvt_f32_ubyte3_e32 v46, v54
	v_mul_f32_e32 v46, 0x3b808081, v46
	v_mul_f32_e32 v49, v49, v46
	v_cvt_f32_ubyte0_e32 v46, v55
	v_mul_f32_e32 v46, 0x3b808081, v46
	v_mul_f32_e32 v54, v42, v46
	v_cvt_f32_ubyte1_e32 v42, v55
	v_mul_f32_e32 v42, 0x3b808081, v42
	v_mul_f32_e32 v58, v43, v42
	v_cvt_f32_ubyte2_e32 v42, v55
	v_mul_f32_e32 v42, 0x3b808081, v42
	v_mul_f32_e32 v59, v44, v42
	v_cvt_f32_ubyte3_e32 v42, v55
	v_mul_f32_e32 v42, 0x3b808081, v42
	v_mul_f32_e32 v45, v45, v42
	v_lshl_add_u64 v[42:43], s[12:13], 0, v[52:53]
	v_lshl_add_u64 v[46:47], v[42:43], 0, v[126:127]
	v_cvt_pk_bf16_f32 v42, v56, v57
	v_cvt_pk_bf16_f32 v43, v48, v49
	v_cvt_pk_bf16_f32 v44, v54, v58
	v_cvt_pk_bf16_f32 v45, v59, v45
	global_store_dwordx4 v[46:47], v[42:45], off
	s_waitcnt vmcnt(15)
; __device__ __forceinline__ unsigned cvt_pk_bf16(float lo, float hi) { unsigned r; asm volatile("v_cvt_pk_bf16_f32 %0, %1, %2" : "=v"(r) : "v"(lo), "v"(hi)); return r; }
; __device__ __forceinline__ float bf_lo(unsigned w) { return __uint_as_float(w << 16); }
; __device__ __forceinline__ float bf_hi(unsigned w) { return __uint_as_float(w & 0xffff0000u); }
;     __device__ __forceinline__ void operator()(const f32x4 (&acc)[2][2][4][2], const Unit& u, int wr, int wc, int fr, int fq) const {
;         const int row0 = u.pm * BM + wr * 64 + fr, col0 = u.pn * BM + wc * 32 + 8 * fq;
; #pragma unroll
;         for (int ai = 0; ai < 2; ++ai)
; #pragma unroll
;             for (int m = 0; m < 4; ++m) { const size_t row = (size_t)(row0 + ai * HALF + m * 16);
; #pragma unroll
;                 for (int bj = 0; bj < 2; ++bj) { const f32x4 v0 = acc[ai][bj][m][0], v1 = acc[ai][bj][m][1];
;                     const u32x2 g = *(const u32x2*)(G + row * ldg + col0 + bj * HALF);
;                     float o[8]; const float k255 = 1.0f / 255.0f;
;                     o[0] = v0[0] * ((float)(g.x & 0xffu) * k255); o[1] = v0[1] * ((float)((g.x >> 8) & 0xffu) * k255); o[2] = v0[2] * ((float)((g.x >> 16) & 0xffu) * k255); o[3] = v0[3] * ((float)(g.x >> 24) * k255);
;                     o[4] = v1[0] * ((float)(g.y & 0xffu) * k255); o[5] = v1[1] * ((float)((g.y >> 8) & 0xffu) * k255); o[6] = v1[2] * ((float)((g.y >> 16) & 0xffu) * k255); o[7] = v1[3] * ((float)(g.y >> 24) * k255);
;                     bf16_t* dst = MG + row * 1024 + col0 + bj * HALF;
;                     if (SECOND) { const u32x4 p = *(const u32x4*)dst;
;                         o[0] += bf_lo(p.x); o[1] += bf_hi(p.x); o[2] += bf_lo(p.y); o[3] += bf_hi(p.y); o[4] += bf_lo(p.z); o[5] += bf_hi(p.z); o[6] += bf_lo(p.w); o[7] += bf_hi(p.w); }
;                     u32x4 w; w.x = cvt_pk_bf16(o[0], o[1]); w.y = cvt_pk_bf16(o[2], o[3]); w.z = cvt_pk_bf16(o[4], o[5]); w.w = cvt_pk_bf16(o[6], o[7]);
;                     *(u32x4*)dst = w; } }
	s_nop 1
	v_mov_b32_e32 v42, v222
	v_mov_b32_e32 v43, v223
	v_cvt_f32_ubyte0_e32 v44, v42
	v_mul_f32_e32 v44, 0x3b808081, v44
	v_mul_f32_e32 v38, v38, v44
	v_cvt_f32_ubyte1_e32 v44, v42
	v_mul_f32_e32 v44, 0x3b808081, v44
	v_mul_f32_e32 v39, v39, v44
	v_cvt_f32_ubyte2_e32 v44, v42
	v_cvt_f32_ubyte3_e32 v42, v42
	v_mul_f32_e32 v42, 0x3b808081, v42
	v_mul_f32_e32 v41, v41, v42
	v_cvt_f32_ubyte0_e32 v42, v43
	v_mul_f32_e32 v42, 0x3b808081, v42
	v_mul_f32_e32 v42, v34, v42
	v_cvt_f32_ubyte1_e32 v34, v43
	v_mul_f32_e32 v44, 0x3b808081, v44
	v_mul_f32_e32 v34, 0x3b808081, v34
	v_mul_f32_e32 v40, v40, v44
	v_mul_f32_e32 v44, v35, v34
	v_cvt_f32_ubyte2_e32 v34, v43
	v_mul_f32_e32 v34, 0x3b808081, v34
	v_mul_f32_e32 v45, v36, v34
	v_cvt_f32_ubyte3_e32 v34, v43
	v_mul_f32_e32 v34, 0x3b808081, v34
	v_mul_f32_e32 v37, v37, v34
	v_cvt_pk_bf16_f32 v34, v38, v39
	v_cvt_pk_bf16_f32 v35, v40, v41
	v_cvt_pk_bf16_f32 v36, v42, v44
	v_cvt_pk_bf16_f32 v37, v45, v37
	global_store_dwordx4 v[46:47], v[34:37], off offset:256
	s_nop 1
	v_lshl_add_u64 v[36:37], v[148:149], 0, s[20:21]
	v_lshl_add_u64 v[34:35], s[14:15], 0, v[36:37]
	v_lshl_add_u64 v[34:35], v[34:35], 0, v[146:147]
	s_mov_b64 s[20:21], 0x58000
	s_waitcnt vmcnt(14)
	s_nop 1
	v_mov_b32_e32 v38, v200
	v_mov_b32_e32 v39, v201
	v_cvt_f32_ubyte0_e32 v40, v38
	v_mul_f32_e32 v40, 0x3b808081, v40
	v_mul_f32_e32 v40, v30, v40
	v_cvt_f32_ubyte1_e32 v30, v38
	v_mul_f32_e32 v30, 0x3b808081, v30
	v_mul_f32_e32 v41, v31, v30
	v_cvt_f32_ubyte2_e32 v30, v38
	v_mul_f32_e32 v30, 0x3b808081, v30
	v_mul_f32_e32 v32, v32, v30
	v_cvt_f32_ubyte3_e32 v30, v38
	v_mul_f32_e32 v30, 0x3b808081, v30
	v_mul_f32_e32 v33, v33, v30
	v_cvt_f32_ubyte0_e32 v30, v39
	v_mul_f32_e32 v30, 0x3b808081, v30
	v_mul_f32_e32 v38, v26, v30
	v_cvt_f32_ubyte1_e32 v26, v39
	v_mul_f32_e32 v26, 0x3b808081, v26
	v_mul_f32_e32 v42, v27, v26
	v_cvt_f32_ubyte2_e32 v26, v39
	v_mul_f32_e32 v26, 0x3b808081, v26
	v_mul_f32_e32 v43, v28, v26
	v_cvt_f32_ubyte3_e32 v26, v39
	v_mul_f32_e32 v26, 0x3b808081, v26
	v_mul_f32_e32 v29, v29, v26
	v_lshl_add_u64 v[26:27], s[12:13], 0, v[36:37]
	v_lshl_add_u64 v[30:31], v[26:27], 0, v[126:127]
	v_cvt_pk_bf16_f32 v26, v40, v41
	v_cvt_pk_bf16_f32 v27, v32, v33
	v_cvt_pk_bf16_f32 v28, v38, v42
	v_cvt_pk_bf16_f32 v29, v43, v29
	global_store_dwordx4 v[30:31], v[26:29], off
	s_waitcnt vmcnt(14)
	s_nop 1
	v_mov_b32_e32 v26, v202
	v_mov_b32_e32 v27, v203
	v_cvt_f32_ubyte0_e32 v28, v26
	v_mul_f32_e32 v28, 0x3b808081, v28
	v_mul_f32_e32 v22, v22, v28
	v_cvt_f32_ubyte1_e32 v28, v26
	v_mul_f32_e32 v28, 0x3b808081, v28
	v_mul_f32_e32 v23, v23, v28
	v_cvt_f32_ubyte2_e32 v28, v26
	v_cvt_f32_ubyte3_e32 v26, v26
	v_mul_f32_e32 v26, 0x3b808081, v26
	v_mul_f32_e32 v25, v25, v26
	v_cvt_f32_ubyte0_e32 v26, v27
	v_mul_f32_e32 v26, 0x3b808081, v26
	v_mul_f32_e32 v26, v18, v26
	v_cvt_f32_ubyte1_e32 v18, v27
	v_mul_f32_e32 v28, 0x3b808081, v28
	v_mul_f32_e32 v18, 0x3b808081, v18
	v_mul_f32_e32 v24, v24, v28
	v_mul_f32_e32 v28, v19, v18
	v_cvt_f32_ubyte2_e32 v18, v27
	v_mul_f32_e32 v18, 0x3b808081, v18
	v_mul_f32_e32 v29, v20, v18
	v_cvt_f32_ubyte3_e32 v18, v27
	v_mul_f32_e32 v18, 0x3b808081, v18
	v_mul_f32_e32 v21, v21, v18
	v_cvt_pk_bf16_f32 v18, v22, v23
	v_cvt_pk_bf16_f32 v19, v24, v25
	v_cvt_pk_bf16_f32 v20, v26, v28
	v_cvt_pk_bf16_f32 v21, v29, v21
	global_store_dwordx4 v[30:31], v[18:21], off offset:256
	s_nop 1
	v_lshl_add_u64 v[20:21], v[148:149], 0, s[20:21]
	v_lshl_add_u64 v[18:19], s[14:15], 0, v[20:21]
	v_lshl_add_u64 v[18:19], v[18:19], 0, v[146:147]
	s_mov_b64 s[20:21], -1
	s_waitcnt vmcnt(12)
	s_nop 1
	v_mov_b32_e32 v22, v204
	v_mov_b32_e32 v23, v205
	v_cvt_f32_ubyte0_e32 v24, v22
	v_mul_f32_e32 v24, 0x3b808081, v24
	v_mul_f32_e32 v24, v14, v24
	v_cvt_f32_ubyte1_e32 v14, v22
	v_mul_f32_e32 v14, 0x3b808081, v14
	v_mul_f32_e32 v25, v15, v14
	v_cvt_f32_ubyte2_e32 v14, v22
	v_mul_f32_e32 v14, 0x3b808081, v14
	v_mul_f32_e32 v16, v16, v14
	v_cvt_f32_ubyte3_e32 v14, v22
	v_mul_f32_e32 v14, 0x3b808081, v14
	v_mul_f32_e32 v17, v17, v14
	v_cvt_f32_ubyte0_e32 v14, v23
	v_mul_f32_e32 v14, 0x3b808081, v14
	v_mul_f32_e32 v22, v10, v14
	v_cvt_f32_ubyte1_e32 v10, v23
	v_mul_f32_e32 v10, 0x3b808081, v10
	v_mul_f32_e32 v26, v11, v10
	v_cvt_f32_ubyte2_e32 v10, v23
	v_mul_f32_e32 v10, 0x3b808081, v10
	v_mul_f32_e32 v27, v12, v10
	v_cvt_f32_ubyte3_e32 v10, v23
	v_mul_f32_e32 v10, 0x3b808081, v10
	v_mul_f32_e32 v13, v13, v10
	v_lshl_add_u64 v[10:11], s[12:13], 0, v[20:21]
	v_lshl_add_u64 v[14:15], v[10:11], 0, v[126:127]
	v_cvt_pk_bf16_f32 v10, v24, v25
	v_cvt_pk_bf16_f32 v11, v16, v17
	v_cvt_pk_bf16_f32 v12, v22, v26
	v_cvt_pk_bf16_f32 v13, v27, v13
	global_store_dwordx4 v[14:15], v[10:13], off
	s_waitcnt vmcnt(12)
	s_nop 1
	v_mov_b32_e32 v10, v206
	v_mov_b32_e32 v11, v207
	v_cvt_f32_ubyte0_e32 v12, v10
	v_mul_f32_e32 v12, 0x3b808081, v12
	v_mul_f32_e32 v6, v6, v12
	v_cvt_f32_ubyte1_e32 v12, v10
	v_mul_f32_e32 v12, 0x3b808081, v12
	v_mul_f32_e32 v7, v7, v12
	v_cvt_f32_ubyte2_e32 v12, v10
	v_cvt_f32_ubyte3_e32 v10, v10
	v_mul_f32_e32 v10, 0x3b808081, v10
	v_mul_f32_e32 v9, v9, v10
	v_cvt_f32_ubyte0_e32 v10, v11
	v_mul_f32_e32 v10, 0x3b808081, v10
	v_mul_f32_e32 v10, v2, v10
	v_cvt_f32_ubyte1_e32 v2, v11
	v_mul_f32_e32 v12, 0x3b808081, v12
	v_mul_f32_e32 v2, 0x3b808081, v2
	v_mul_f32_e32 v8, v8, v12
	v_mul_f32_e32 v12, v3, v2
	v_cvt_f32_ubyte2_e32 v2, v11
	v_mul_f32_e32 v2, 0x3b808081, v2
	v_mul_f32_e32 v13, v4, v2
	v_cvt_f32_ubyte3_e32 v2, v11
	v_mul_f32_e32 v2, 0x3b808081, v2
	v_mul_f32_e32 v5, v5, v2
	v_cvt_pk_bf16_f32 v2, v6, v7
	v_cvt_pk_bf16_f32 v3, v8, v9
	v_cvt_pk_bf16_f32 v4, v10, v12
	v_cvt_pk_bf16_f32 v5, v13, v5
	global_store_dwordx4 v[14:15], v[2:5], off offset:256
	s_cbranch_vccnz .LBB0_676
	s_andn2_b64 vcc, exec, s[10:11]
	s_cbranch_vccnz .LBB0_675
	s_barrier
	s_branch .LBB0_675

; __device__ __forceinline__ unsigned cvt_pk_bf16(float lo, float hi) { unsigned r; asm volatile("v_cvt_pk_bf16_f32 %0, %1, %2" : "=v"(r) : "v"(lo), "v"(hi)); return r; }
; __device__ __forceinline__ float bf_lo(unsigned w) { return __uint_as_float(w << 16); }
; __device__ __forceinline__ float bf_hi(unsigned w) { return __uint_as_float(w & 0xffff0000u); }
;     __device__ __forceinline__ void operator()(const f32x4 (&acc)[2][2][4][2], const Unit& u, int wr, int wc, int fr, int fq) const {
;         const int row0 = u.pm * BM + wr * 64 + fr, col0 = u.pn * BM + wc * 32 + 8 * fq;
; #pragma unroll
;         for (int ai = 0; ai < 2; ++ai)
; #pragma unroll
;             for (int m = 0; m < 4; ++m) { const size_t row = (size_t)(row0 + ai * HALF + m * 16);
; #pragma unroll
;                 for (int bj = 0; bj < 2; ++bj) { const f32x4 v0 = acc[ai][bj][m][0], v1 = acc[ai][bj][m][1];
;                     const u32x2 g = *(const u32x2*)(G + row * ldg + col0 + bj * HALF);
;                     float o[8]; const float k255 = 1.0f / 255.0f;
;                     o[0] = v0[0] * ((float)(g.x & 0xffu) * k255); o[1] = v0[1] * ((float)((g.x >> 8) & 0xffu) * k255); o[2] = v0[2] * ((float)((g.x >> 16) & 0xffu) * k255); o[3] = v0[3] * ((float)(g.x >> 24) * k255);
;                     o[4] = v1[0] * ((float)(g.y & 0xffu) * k255); o[5] = v1[1] * ((float)((g.y >> 8) & 0xffu) * k255); o[6] = v1[2] * ((float)((g.y >> 16) & 0xffu) * k255); o[7] = v1[3] * ((float)(g.y >> 24) * k255);
;                     bf16_t* dst = MG + row * 1024 + col0 + bj * HALF;
;                     if (SECOND) { const u32x4 p = *(const u32x4*)dst;
;                         o[0] += bf_lo(p.x); o[1] += bf_hi(p.x); o[2] += bf_lo(p.y); o[3] += bf_hi(p.y); o[4] += bf_lo(p.z); o[5] += bf_hi(p.z); o[6] += bf_lo(p.w); o[7] += bf_hi(p.w); }
;                     u32x4 w; w.x = cvt_pk_bf16(o[0], o[1]); w.y = cvt_pk_bf16(o[2], o[3]); w.z = cvt_pk_bf16(o[4], o[5]); w.w = cvt_pk_bf16(o[6], o[7]);
;                     *(u32x4*)dst = w; } }
.LBB0_703:
	v_lshl_add_u32 v152, s58, 8, v1
	v_ashrrev_i32_e32 v153, 31, v152
	v_lshl_or_b32 v148, s26, 8, v157
	v_lshlrev_b64 v[150:151], 11, v[152:153]
	v_ashrrev_i32_e32 v149, 31, v148
	v_lshl_add_u64 v[146:147], s[12:13], 0, v[150:151]
	v_lshl_add_u64 v[164:165], v[146:147], 0, v[148:149]
	global_load_dwordx2 v[146:147], v[164:165], off offset:1024
	s_mov_b64 s[26:27], 0x48000
	s_andn2_b64 vcc, exec, s[4:5]
	s_waitcnt vmcnt(0)
	v_cvt_f32_ubyte1_e32 v154, v146
	v_cvt_f32_ubyte0_e32 v153, v146
	v_mul_f32_e32 v159, 0x3b808081, v154
	v_cvt_f32_ubyte2_e32 v154, v146
	v_cvt_f32_ubyte3_e32 v146, v146
	v_mul_f32_e32 v167, 0x3b808081, v146
	v_cvt_f32_ubyte0_e32 v146, v147
	v_mul_f32_e32 v168, 0x3b808081, v146
	v_cvt_f32_ubyte1_e32 v146, v147
	v_mul_f32_e32 v169, 0x3b808081, v146
	v_cvt_f32_ubyte2_e32 v146, v147
	v_mul_f32_e32 v170, 0x3b808081, v146
	v_cvt_f32_ubyte3_e32 v146, v147
	v_mul_f32_e32 v166, 0x3b808081, v154
	v_mul_f32_e32 v171, 0x3b808081, v146
	v_lshl_add_u64 v[154:155], s[6:7], 0, v[150:151]
	v_lshlrev_b64 v[146:147], 1, v[148:149]
	v_lshl_add_u64 v[154:155], v[154:155], 0, v[146:147]
	s_mov_b32 s77, 0
	v_mov_b32_e32 v252, v164
	v_mov_b32_e32 v253, v165
	v_mov_b32_e32 v248, v154
	v_mov_b32_e32 v249, v155
	global_load_dwordx2 v[206:207], v[252:253], off offset:1152 nt
	global_load_dwordx4 v[202:205], v[248:249], off
	global_load_dwordx4 v[208:211], v[248:249], off offset:256
	s_mov_b32 s76, 0x8000
	v_lshl_add_u64 v[250:251], v[252:253], 0, s[76:77]
	global_load_dwordx2 v[212:213], v[250:251], off offset:1024 nt
	global_load_dwordx2 v[218:219], v[250:251], off offset:1152 nt
	s_mov_b32 s76, 0x8000
	v_lshl_add_u64 v[250:251], v[248:249], 0, s[76:77]
	global_load_dwordx4 v[214:217], v[250:251], off
	global_load_dwordx4 v[220:223], v[250:251], off offset:256
	s_mov_b32 s76, 0x10000
	v_lshl_add_u64 v[250:251], v[252:253], 0, s[76:77]
	global_load_dwordx2 v[224:225], v[250:251], off offset:1024 nt
	global_load_dwordx2 v[230:231], v[250:251], off offset:1152 nt
	s_mov_b32 s76, 0x10000
	v_lshl_add_u64 v[250:251], v[248:249], 0, s[76:77]
	global_load_dwordx4 v[226:229], v[250:251], off
	global_load_dwordx4 v[232:235], v[250:251], off offset:256
	s_mov_b32 s76, 0x18000
	v_lshl_add_u64 v[250:251], v[252:253], 0, s[76:77]
	global_load_dwordx2 v[236:237], v[250:251], off offset:1024 nt
	global_load_dwordx2 v[242:243], v[250:251], off offset:1152 nt
	s_mov_b32 s76, 0x18000
	v_lshl_add_u64 v[250:251], v[248:249], 0, s[76:77]
	global_load_dwordx4 v[238:241], v[250:251], off
	global_load_dwordx4 v[244:247], v[250:251], off offset:256
	v_mul_f32_e32 v153, 0x3b808081, v153
	s_waitcnt vmcnt(13)
	s_nop 1
	v_mov_b32_e32 v160, v202
	v_mov_b32_e32 v161, v203
	v_mov_b32_e32 v162, v204
	v_mov_b32_e32 v163, v205
	v_lshlrev_b32_e32 v172, 16, v160
	v_fmac_f32_e32 v172, v130, v153
	v_and_b32_e32 v130, 0xffff0000, v160
	v_fmac_f32_e32 v130, v131, v159
	v_lshlrev_b32_e32 v131, 16, v161
	v_fmac_f32_e32 v131, v132, v166
	v_and_b32_e32 v132, 0xffff0000, v161
	v_fmac_f32_e32 v132, v133, v167
	v_lshlrev_b32_e32 v133, 16, v162
	v_and_b32_e32 v153, 0xffff0000, v162
	v_lshlrev_b32_e32 v159, 16, v163
	v_and_b32_e32 v160, 0xffff0000, v163
	v_fmac_f32_e32 v133, v126, v168
	v_fmac_f32_e32 v153, v127, v169
	v_fmac_f32_e32 v159, v128, v170
	v_fmac_f32_e32 v160, v129, v171
	v_cvt_pk_bf16_f32 v126, v172, v130
	v_cvt_pk_bf16_f32 v127, v131, v132
	v_cvt_pk_bf16_f32 v128, v133, v153
	v_cvt_pk_bf16_f32 v129, v159, v160
	global_store_dwordx4 v[154:155], v[126:129], off
	s_waitcnt vmcnt(15)
	s_nop 1
	v_mov_b32_e32 v126, v206
	v_mov_b32_e32 v127, v207
	v_cvt_f32_ubyte0_e32 v128, v126
	v_mul_f32_e32 v130, 0x3b808081, v128
	v_cvt_f32_ubyte1_e32 v128, v126
	v_mul_f32_e32 v131, 0x3b808081, v128
	v_cvt_f32_ubyte2_e32 v128, v126
	v_cvt_f32_ubyte3_e32 v126, v126
	v_mul_f32_e32 v133, 0x3b808081, v126
	v_cvt_f32_ubyte0_e32 v126, v127
	v_mul_f32_e32 v153, 0x3b808081, v126
	v_cvt_f32_ubyte1_e32 v126, v127
	v_mul_f32_e32 v159, 0x3b808081, v126
	v_cvt_f32_ubyte2_e32 v126, v127
	v_mul_f32_e32 v160, 0x3b808081, v126
	v_cvt_f32_ubyte3_e32 v126, v127
	v_mul_f32_e32 v132, 0x3b808081, v128
	v_mul_f32_e32 v161, 0x3b808081, v126
	s_waitcnt vmcnt(13)
	s_nop 1
	v_mov_b32_e32 v126, v208
	v_mov_b32_e32 v127, v209
	v_mov_b32_e32 v128, v210
	v_mov_b32_e32 v129, v211
	s_mov_b32 s76, 0x40000
	v_lshl_add_u64 v[250:251], v[252:253], 0, s[76:77]
	global_load_dwordx2 v[200:201], v[250:251], off offset:1024 nt
	global_load_dwordx2 v[206:207], v[250:251], off offset:1152 nt
	s_mov_b32 s76, 0x40000
	v_lshl_add_u64 v[250:251], v[248:249], 0, s[76:77]
	global_load_dwordx4 v[202:205], v[250:251], off
	global_load_dwordx4 v[208:211], v[250:251], off offset:256
	v_lshlrev_b32_e32 v162, 16, v126
	v_fmac_f32_e32 v162, v122, v130
	v_and_b32_e32 v122, 0xffff0000, v126
	v_fmac_f32_e32 v122, v123, v131
	v_lshlrev_b32_e32 v123, 16, v127
	v_fmac_f32_e32 v123, v124, v132
	v_and_b32_e32 v124, 0xffff0000, v127
	v_fmac_f32_e32 v124, v125, v133
	v_lshlrev_b32_e32 v125, 16, v128
	v_fmac_f32_e32 v125, v118, v153
	v_and_b32_e32 v126, 0xffff0000, v128
	v_lshlrev_b32_e32 v127, 16, v129
	v_and_b32_e32 v128, 0xffff0000, v129
	v_cvt_pk_bf16_f32 v118, v162, v122
	v_fmac_f32_e32 v126, v119, v159
	v_fmac_f32_e32 v127, v120, v160
	v_fmac_f32_e32 v128, v121, v161
	v_cvt_pk_bf16_f32 v119, v123, v124
	v_cvt_pk_bf16_f32 v120, v125, v126
	v_cvt_pk_bf16_f32 v121, v127, v128
	global_store_dwordx4 v[154:155], v[118:121], off offset:256
	s_nop 1
	v_or_b32_e32 v118, 16, v152
	v_ashrrev_i32_e32 v119, 31, v118
	v_lshlrev_b64 v[120:121], 11, v[118:119]
	v_lshl_add_u64 v[118:119], s[12:13], 0, v[120:121]
	v_lshl_add_u64 v[118:119], v[118:119], 0, v[148:149]
	v_lshl_add_u64 v[120:121], s[6:7], 0, v[120:121]
	v_lshl_add_u64 v[120:121], v[120:121], 0, v[146:147]
	s_waitcnt vmcnt(17)
; __device__ __forceinline__ unsigned cvt_pk_bf16(float lo, float hi) { unsigned r; asm volatile("v_cvt_pk_bf16_f32 %0, %1, %2" : "=v"(r) : "v"(lo), "v"(hi)); return r; }
; __device__ __forceinline__ float bf_lo(unsigned w) { return __uint_as_float(w << 16); }
; __device__ __forceinline__ float bf_hi(unsigned w) { return __uint_as_float(w & 0xffff0000u); }
;     __device__ __forceinline__ void operator()(const f32x4 (&acc)[2][2][4][2], const Unit& u, int wr, int wc, int fr, int fq) const {
;         const int row0 = u.pm * BM + wr * 64 + fr, col0 = u.pn * BM + wc * 32 + 8 * fq;
; #pragma unroll
;         for (int ai = 0; ai < 2; ++ai)
; #pragma unroll
;             for (int m = 0; m < 4; ++m) { const size_t row = (size_t)(row0 + ai * HALF + m * 16);
; #pragma unroll
;                 for (int bj = 0; bj < 2; ++bj) { const f32x4 v0 = acc[ai][bj][m][0], v1 = acc[ai][bj][m][1];
;                     const u32x2 g = *(const u32x2*)(G + row * ldg + col0 + bj * HALF);
;                     float o[8]; const float k255 = 1.0f / 255.0f;
;                     o[0] = v0[0] * ((float)(g.x & 0xffu) * k255); o[1] = v0[1] * ((float)((g.x >> 8) & 0xffu) * k255); o[2] = v0[2] * ((float)((g.x >> 16) & 0xffu) * k255); o[3] = v0[3] * ((float)(g.x >> 24) * k255);
;                     o[4] = v1[0] * ((float)(g.y & 0xffu) * k255); o[5] = v1[1] * ((float)((g.y >> 8) & 0xffu) * k255); o[6] = v1[2] * ((float)((g.y >> 16) & 0xffu) * k255); o[7] = v1[3] * ((float)(g.y >> 24) * k255);
;                     bf16_t* dst = MG + row * 1024 + col0 + bj * HALF;
;                     if (SECOND) { const u32x4 p = *(const u32x4*)dst;
;                         o[0] += bf_lo(p.x); o[1] += bf_hi(p.x); o[2] += bf_lo(p.y); o[3] += bf_hi(p.y); o[4] += bf_lo(p.z); o[5] += bf_hi(p.z); o[6] += bf_lo(p.w); o[7] += bf_hi(p.w); }
;                     u32x4 w; w.x = cvt_pk_bf16(o[0], o[1]); w.y = cvt_pk_bf16(o[2], o[3]); w.z = cvt_pk_bf16(o[4], o[5]); w.w = cvt_pk_bf16(o[6], o[7]);
;                     *(u32x4*)dst = w; } }
	s_nop 1
	v_mov_b32_e32 v122, v212
	v_mov_b32_e32 v123, v213
	v_cvt_f32_ubyte0_e32 v124, v122
	v_mul_f32_e32 v126, 0x3b808081, v124
	v_cvt_f32_ubyte1_e32 v124, v122
	v_mul_f32_e32 v127, 0x3b808081, v124
	v_cvt_f32_ubyte2_e32 v124, v122
	v_cvt_f32_ubyte3_e32 v122, v122
	v_mul_f32_e32 v129, 0x3b808081, v122
	v_cvt_f32_ubyte0_e32 v122, v123
	v_mul_f32_e32 v130, 0x3b808081, v122
	v_cvt_f32_ubyte1_e32 v122, v123
	v_mul_f32_e32 v131, 0x3b808081, v122
	v_cvt_f32_ubyte2_e32 v122, v123
	v_mul_f32_e32 v132, 0x3b808081, v122
	v_cvt_f32_ubyte3_e32 v122, v123
	v_mul_f32_e32 v128, 0x3b808081, v124
	v_mul_f32_e32 v133, 0x3b808081, v122
	s_waitcnt vmcnt(15)
	s_nop 1
	v_mov_b32_e32 v122, v214
	v_mov_b32_e32 v123, v215
	v_mov_b32_e32 v124, v216
	v_mov_b32_e32 v125, v217
	v_lshlrev_b32_e32 v153, 16, v122
	v_fmac_f32_e32 v153, v114, v126
	v_and_b32_e32 v114, 0xffff0000, v122
	v_fmac_f32_e32 v114, v115, v127
	v_lshlrev_b32_e32 v115, 16, v123
	v_fmac_f32_e32 v115, v116, v128
	v_and_b32_e32 v116, 0xffff0000, v123
	v_fmac_f32_e32 v116, v117, v129
	v_lshlrev_b32_e32 v117, 16, v124
	v_and_b32_e32 v122, 0xffff0000, v124
	v_lshlrev_b32_e32 v123, 16, v125
	v_and_b32_e32 v124, 0xffff0000, v125
	v_fmac_f32_e32 v117, v110, v130
	v_fmac_f32_e32 v122, v111, v131
	v_fmac_f32_e32 v123, v112, v132
	v_fmac_f32_e32 v124, v113, v133
	v_cvt_pk_bf16_f32 v110, v153, v114
	v_cvt_pk_bf16_f32 v111, v115, v116
	v_cvt_pk_bf16_f32 v112, v117, v122
	v_cvt_pk_bf16_f32 v113, v123, v124
	global_store_dwordx4 v[120:121], v[110:113], off
	s_waitcnt vmcnt(17)
	s_nop 1
	v_mov_b32_e32 v110, v218
	v_mov_b32_e32 v111, v219
	v_cvt_f32_ubyte0_e32 v112, v110
	v_mul_f32_e32 v114, 0x3b808081, v112
	v_cvt_f32_ubyte1_e32 v112, v110
	v_mul_f32_e32 v115, 0x3b808081, v112
	v_cvt_f32_ubyte2_e32 v112, v110
	v_cvt_f32_ubyte3_e32 v110, v110
	v_mul_f32_e32 v117, 0x3b808081, v110
	v_cvt_f32_ubyte0_e32 v110, v111
	v_mul_f32_e32 v118, 0x3b808081, v110
	v_cvt_f32_ubyte1_e32 v110, v111
	v_mul_f32_e32 v119, 0x3b808081, v110
	v_cvt_f32_ubyte2_e32 v110, v111
	v_mul_f32_e32 v122, 0x3b808081, v110
	v_cvt_f32_ubyte3_e32 v110, v111
	v_mul_f32_e32 v116, 0x3b808081, v112
	v_mul_f32_e32 v123, 0x3b808081, v110
	s_waitcnt vmcnt(15)
	s_nop 1
	v_mov_b32_e32 v110, v220
	v_mov_b32_e32 v111, v221
	v_mov_b32_e32 v112, v222
	v_mov_b32_e32 v113, v223
	s_mov_b32 s76, 0x48000
	v_lshl_add_u64 v[250:251], v[252:253], 0, s[76:77]
	global_load_dwordx2 v[212:213], v[250:251], off offset:1024 nt
	global_load_dwordx2 v[218:219], v[250:251], off offset:1152 nt
	s_mov_b32 s76, 0x48000
	v_lshl_add_u64 v[250:251], v[248:249], 0, s[76:77]
	global_load_dwordx4 v[214:217], v[250:251], off
	global_load_dwordx4 v[220:223], v[250:251], off offset:256
	v_lshlrev_b32_e32 v124, 16, v110
	v_fmac_f32_e32 v124, v106, v114
	v_and_b32_e32 v106, 0xffff0000, v110
	v_fmac_f32_e32 v106, v107, v115
	v_lshlrev_b32_e32 v107, 16, v111
	v_fmac_f32_e32 v107, v108, v116
	v_and_b32_e32 v108, 0xffff0000, v111
	v_fmac_f32_e32 v108, v109, v117
	v_lshlrev_b32_e32 v109, 16, v112
	v_fmac_f32_e32 v109, v102, v118
	v_and_b32_e32 v110, 0xffff0000, v112
	v_lshlrev_b32_e32 v111, 16, v113
	v_and_b32_e32 v112, 0xffff0000, v113
	v_cvt_pk_bf16_f32 v102, v124, v106
	v_fmac_f32_e32 v110, v103, v119
	v_fmac_f32_e32 v111, v104, v122
	v_fmac_f32_e32 v112, v105, v123
	v_cvt_pk_bf16_f32 v103, v107, v108
	v_cvt_pk_bf16_f32 v104, v109, v110
	v_cvt_pk_bf16_f32 v105, v111, v112
	global_store_dwordx4 v[120:121], v[102:105], off offset:256
	s_nop 1
	v_or_b32_e32 v102, 32, v152
	v_ashrrev_i32_e32 v103, 31, v102
	v_lshlrev_b64 v[104:105], 11, v[102:103]
	v_lshl_add_u64 v[102:103], s[12:13], 0, v[104:105]
	v_lshl_add_u64 v[102:103], v[102:103], 0, v[148:149]
	v_lshl_add_u64 v[104:105], s[6:7], 0, v[104:105]
	v_lshl_add_u64 v[104:105], v[104:105], 0, v[146:147]
	s_waitcnt vmcnt(19)
	s_nop 1
	v_mov_b32_e32 v106, v224
	v_mov_b32_e32 v107, v225
	v_cvt_f32_ubyte0_e32 v108, v106
	v_mul_f32_e32 v110, 0x3b808081, v108
	v_cvt_f32_ubyte1_e32 v108, v106
	v_mul_f32_e32 v111, 0x3b808081, v108
	v_cvt_f32_ubyte2_e32 v108, v106
	v_cvt_f32_ubyte3_e32 v106, v106
	v_mul_f32_e32 v113, 0x3b808081, v106
	v_cvt_f32_ubyte0_e32 v106, v107
	v_mul_f32_e32 v114, 0x3b808081, v106
	v_cvt_f32_ubyte1_e32 v106, v107
	v_mul_f32_e32 v115, 0x3b808081, v106
	v_cvt_f32_ubyte2_e32 v106, v107
	v_mul_f32_e32 v116, 0x3b808081, v106
	v_cvt_f32_ubyte3_e32 v106, v107
	v_mul_f32_e32 v112, 0x3b808081, v108
	v_mul_f32_e32 v117, 0x3b808081, v106
	s_waitcnt vmcnt(17)
	s_nop 1
	v_mov_b32_e32 v106, v226
	v_mov_b32_e32 v107, v227
	v_mov_b32_e32 v108, v228
	v_mov_b32_e32 v109, v229
	v_lshlrev_b32_e32 v118, 16, v106
	v_fmac_f32_e32 v118, v98, v110
	v_and_b32_e32 v98, 0xffff0000, v106
	v_fmac_f32_e32 v98, v99, v111
	v_lshlrev_b32_e32 v99, 16, v107
	v_fmac_f32_e32 v99, v100, v112
	v_and_b32_e32 v100, 0xffff0000, v107
	v_fmac_f32_e32 v100, v101, v113
	v_lshlrev_b32_e32 v101, 16, v108
	v_and_b32_e32 v106, 0xffff0000, v108
	v_lshlrev_b32_e32 v107, 16, v109
	v_and_b32_e32 v108, 0xffff0000, v109
	v_fmac_f32_e32 v101, v94, v114
	v_fmac_f32_e32 v106, v95, v115
	v_fmac_f32_e32 v107, v96, v116
	v_fmac_f32_e32 v108, v97, v117
	v_cvt_pk_bf16_f32 v94, v118, v98
	v_cvt_pk_bf16_f32 v95, v99, v100
	v_cvt_pk_bf16_f32 v96, v101, v106
	v_cvt_pk_bf16_f32 v97, v107, v108
	global_store_dwordx4 v[104:105], v[94:97], off
	s_waitcnt vmcnt(19)
	s_nop 1
	v_mov_b32_e32 v94, v230
	v_mov_b32_e32 v95, v231
	v_cvt_f32_ubyte0_e32 v96, v94
	v_mul_f32_e32 v98, 0x3b808081, v96
	v_cvt_f32_ubyte1_e32 v96, v94
	v_mul_f32_e32 v99, 0x3b808081, v96
	v_cvt_f32_ubyte2_e32 v96, v94
	v_cvt_f32_ubyte3_e32 v94, v94
	v_mul_f32_e32 v101, 0x3b808081, v94
	v_cvt_f32_ubyte0_e32 v94, v95
	v_mul_f32_e32 v102, 0x3b808081, v94
	v_cvt_f32_ubyte1_e32 v94, v95
	v_mul_f32_e32 v103, 0x3b808081, v94
	v_cvt_f32_ubyte2_e32 v94, v95
	v_mul_f32_e32 v106, 0x3b808081, v94
	v_cvt_f32_ubyte3_e32 v94, v95
	v_mul_f32_e32 v100, 0x3b808081, v96
	v_mul_f32_e32 v107, 0x3b808081, v94
	s_waitcnt vmcnt(17)
; __device__ __forceinline__ unsigned cvt_pk_bf16(float lo, float hi) { unsigned r; asm volatile("v_cvt_pk_bf16_f32 %0, %1, %2" : "=v"(r) : "v"(lo), "v"(hi)); return r; }
; __device__ __forceinline__ float bf_lo(unsigned w) { return __uint_as_float(w << 16); }
; __device__ __forceinline__ float bf_hi(unsigned w) { return __uint_as_float(w & 0xffff0000u); }
;     __device__ __forceinline__ void operator()(const f32x4 (&acc)[2][2][4][2], const Unit& u, int wr, int wc, int fr, int fq) const {
;         const int row0 = u.pm * BM + wr * 64 + fr, col0 = u.pn * BM + wc * 32 + 8 * fq;
; #pragma unroll
;         for (int ai = 0; ai < 2; ++ai)
; #pragma unroll
;             for (int m = 0; m < 4; ++m) { const size_t row = (size_t)(row0 + ai * HALF + m * 16);
; #pragma unroll
;                 for (int bj = 0; bj < 2; ++bj) { const f32x4 v0 = acc[ai][bj][m][0], v1 = acc[ai][bj][m][1];
;                     const u32x2 g = *(const u32x2*)(G + row * ldg + col0 + bj * HALF);
;                     float o[8]; const float k255 = 1.0f / 255.0f;
;                     o[0] = v0[0] * ((float)(g.x & 0xffu) * k255); o[1] = v0[1] * ((float)((g.x >> 8) & 0xffu) * k255); o[2] = v0[2] * ((float)((g.x >> 16) & 0xffu) * k255); o[3] = v0[3] * ((float)(g.x >> 24) * k255);
;                     o[4] = v1[0] * ((float)(g.y & 0xffu) * k255); o[5] = v1[1] * ((float)((g.y >> 8) & 0xffu) * k255); o[6] = v1[2] * ((float)((g.y >> 16) & 0xffu) * k255); o[7] = v1[3] * ((float)(g.y >> 24) * k255);
;                     bf16_t* dst = MG + row * 1024 + col0 + bj * HALF;
;                     if (SECOND) { const u32x4 p = *(const u32x4*)dst;
;                         o[0] += bf_lo(p.x); o[1] += bf_hi(p.x); o[2] += bf_lo(p.y); o[3] += bf_hi(p.y); o[4] += bf_lo(p.z); o[5] += bf_hi(p.z); o[6] += bf_lo(p.w); o[7] += bf_hi(p.w); }
;                     u32x4 w; w.x = cvt_pk_bf16(o[0], o[1]); w.y = cvt_pk_bf16(o[2], o[3]); w.z = cvt_pk_bf16(o[4], o[5]); w.w = cvt_pk_bf16(o[6], o[7]);
;                     *(u32x4*)dst = w; } }
	s_nop 1
	v_mov_b32_e32 v94, v232
	v_mov_b32_e32 v95, v233
	v_mov_b32_e32 v96, v234
	v_mov_b32_e32 v97, v235
	s_mov_b32 s76, 0x50000
	v_lshl_add_u64 v[250:251], v[252:253], 0, s[76:77]
	global_load_dwordx2 v[224:225], v[250:251], off offset:1024 nt
	global_load_dwordx2 v[230:231], v[250:251], off offset:1152 nt
	s_mov_b32 s76, 0x50000
	v_lshl_add_u64 v[250:251], v[248:249], 0, s[76:77]
	global_load_dwordx4 v[226:229], v[250:251], off
	global_load_dwordx4 v[232:235], v[250:251], off offset:256
	v_lshlrev_b32_e32 v108, 16, v94
	v_fmac_f32_e32 v108, v90, v98
	v_and_b32_e32 v90, 0xffff0000, v94
	v_fmac_f32_e32 v90, v91, v99
	v_lshlrev_b32_e32 v91, 16, v95
	v_fmac_f32_e32 v91, v92, v100
	v_and_b32_e32 v92, 0xffff0000, v95
	v_fmac_f32_e32 v92, v93, v101
	v_lshlrev_b32_e32 v93, 16, v96
	v_fmac_f32_e32 v93, v86, v102
	v_and_b32_e32 v94, 0xffff0000, v96
	v_lshlrev_b32_e32 v95, 16, v97
	v_and_b32_e32 v96, 0xffff0000, v97
	v_cvt_pk_bf16_f32 v86, v108, v90
	v_fmac_f32_e32 v94, v87, v103
	v_fmac_f32_e32 v95, v88, v106
	v_fmac_f32_e32 v96, v89, v107
	v_cvt_pk_bf16_f32 v87, v91, v92
	v_cvt_pk_bf16_f32 v88, v93, v94
	v_cvt_pk_bf16_f32 v89, v95, v96
	global_store_dwordx4 v[104:105], v[86:89], off offset:256
	s_nop 1
	v_or_b32_e32 v86, 48, v152
	v_ashrrev_i32_e32 v87, 31, v86
	v_lshlrev_b64 v[88:89], 11, v[86:87]
	v_lshl_add_u64 v[86:87], s[12:13], 0, v[88:89]
	v_lshl_add_u64 v[86:87], v[86:87], 0, v[148:149]
	v_lshl_add_u64 v[88:89], s[6:7], 0, v[88:89]
	v_lshl_add_u64 v[88:89], v[88:89], 0, v[146:147]
	s_waitcnt vmcnt(21)
	s_nop 1
	v_mov_b32_e32 v90, v236
	v_mov_b32_e32 v91, v237
	v_cvt_f32_ubyte0_e32 v92, v90
	v_mul_f32_e32 v94, 0x3b808081, v92
	v_cvt_f32_ubyte1_e32 v92, v90
	v_mul_f32_e32 v95, 0x3b808081, v92
	v_cvt_f32_ubyte2_e32 v92, v90
	v_cvt_f32_ubyte3_e32 v90, v90
	v_mul_f32_e32 v97, 0x3b808081, v90
	v_cvt_f32_ubyte0_e32 v90, v91
	v_mul_f32_e32 v98, 0x3b808081, v90
	v_cvt_f32_ubyte1_e32 v90, v91
	v_mul_f32_e32 v99, 0x3b808081, v90
	v_cvt_f32_ubyte2_e32 v90, v91
	v_mul_f32_e32 v100, 0x3b808081, v90
	v_cvt_f32_ubyte3_e32 v90, v91
	v_mul_f32_e32 v96, 0x3b808081, v92
	v_mul_f32_e32 v101, 0x3b808081, v90
	s_waitcnt vmcnt(19)
	s_nop 1
	v_mov_b32_e32 v90, v238
	v_mov_b32_e32 v91, v239
	v_mov_b32_e32 v92, v240
	v_mov_b32_e32 v93, v241
	v_lshlrev_b32_e32 v102, 16, v90
	v_fmac_f32_e32 v102, v78, v94
	v_and_b32_e32 v78, 0xffff0000, v90
	v_fmac_f32_e32 v78, v79, v95
	v_lshlrev_b32_e32 v79, 16, v91
	v_fmac_f32_e32 v79, v80, v96
	v_and_b32_e32 v80, 0xffff0000, v91
	v_fmac_f32_e32 v80, v81, v97
	v_lshlrev_b32_e32 v81, 16, v92
	v_and_b32_e32 v90, 0xffff0000, v92
	v_lshlrev_b32_e32 v91, 16, v93
	v_and_b32_e32 v92, 0xffff0000, v93
	v_fmac_f32_e32 v81, v74, v98
	v_fmac_f32_e32 v90, v75, v99
	v_fmac_f32_e32 v91, v76, v100
	v_fmac_f32_e32 v92, v77, v101
	v_cvt_pk_bf16_f32 v74, v102, v78
	v_cvt_pk_bf16_f32 v75, v79, v80
	v_cvt_pk_bf16_f32 v76, v81, v90
	v_cvt_pk_bf16_f32 v77, v91, v92
	global_store_dwordx4 v[88:89], v[74:77], off
	s_waitcnt vmcnt(21)
	s_nop 1
	v_mov_b32_e32 v74, v242
	v_mov_b32_e32 v75, v243
	v_cvt_f32_ubyte0_e32 v76, v74
	v_mul_f32_e32 v78, 0x3b808081, v76
	v_cvt_f32_ubyte1_e32 v76, v74
	v_mul_f32_e32 v79, 0x3b808081, v76
	v_cvt_f32_ubyte2_e32 v76, v74
	v_cvt_f32_ubyte3_e32 v74, v74
	v_mul_f32_e32 v81, 0x3b808081, v74
	v_cvt_f32_ubyte0_e32 v74, v75
	v_mul_f32_e32 v86, 0x3b808081, v74
	v_cvt_f32_ubyte1_e32 v74, v75
	v_mul_f32_e32 v87, 0x3b808081, v74
	v_cvt_f32_ubyte2_e32 v74, v75
	v_mul_f32_e32 v90, 0x3b808081, v74
	v_cvt_f32_ubyte3_e32 v74, v75
	v_mul_f32_e32 v80, 0x3b808081, v76
	v_mul_f32_e32 v91, 0x3b808081, v74
	s_waitcnt vmcnt(19)
	s_nop 1
	v_mov_b32_e32 v74, v244
	v_mov_b32_e32 v75, v245
	v_mov_b32_e32 v76, v246
	v_mov_b32_e32 v77, v247
	s_mov_b32 s76, 0x58000
	v_lshl_add_u64 v[250:251], v[252:253], 0, s[76:77]
	global_load_dwordx2 v[236:237], v[250:251], off offset:1024 nt
	global_load_dwordx2 v[242:243], v[250:251], off offset:1152 nt
	s_mov_b32 s76, 0x58000
	v_lshl_add_u64 v[250:251], v[248:249], 0, s[76:77]
	global_load_dwordx4 v[238:241], v[250:251], off
	global_load_dwordx4 v[244:247], v[250:251], off offset:256
	v_lshlrev_b32_e32 v92, 16, v74
	v_fmac_f32_e32 v92, v70, v78
	v_and_b32_e32 v70, 0xffff0000, v74
	v_fmac_f32_e32 v70, v71, v79
	v_lshlrev_b32_e32 v71, 16, v75
	v_fmac_f32_e32 v71, v72, v80
	v_and_b32_e32 v72, 0xffff0000, v75
	v_fmac_f32_e32 v72, v73, v81
	v_lshlrev_b32_e32 v73, 16, v76
	v_and_b32_e32 v74, 0xffff0000, v76
	v_lshlrev_b32_e32 v75, 16, v77
	v_and_b32_e32 v76, 0xffff0000, v77
	v_fmac_f32_e32 v73, v66, v86
	v_fmac_f32_e32 v74, v67, v87
	v_fmac_f32_e32 v75, v68, v90
	v_fmac_f32_e32 v76, v69, v91
	v_cvt_pk_bf16_f32 v66, v92, v70
	v_cvt_pk_bf16_f32 v67, v71, v72
	v_cvt_pk_bf16_f32 v68, v73, v74
	v_cvt_pk_bf16_f32 v69, v75, v76
	global_store_dwordx4 v[88:89], v[66:69], off offset:256
	s_nop 1
	v_lshl_add_u64 v[68:69], v[150:151], 0, s[68:69]
	v_lshl_add_u64 v[66:67], s[12:13], 0, v[68:69]
	v_lshl_add_u64 v[66:67], v[66:67], 0, v[148:149]
	v_lshl_add_u64 v[68:69], s[6:7], 0, v[68:69]
	v_lshl_add_u64 v[68:69], v[68:69], 0, v[146:147]
	s_waitcnt vmcnt(22)
	s_nop 1
	v_mov_b32_e32 v70, v200
	v_mov_b32_e32 v71, v201
	v_cvt_f32_ubyte0_e32 v72, v70
	v_mul_f32_e32 v74, 0x3b808081, v72
	v_cvt_f32_ubyte1_e32 v72, v70
	v_mul_f32_e32 v75, 0x3b808081, v72
	v_cvt_f32_ubyte2_e32 v72, v70
	v_cvt_f32_ubyte3_e32 v70, v70
	v_mul_f32_e32 v77, 0x3b808081, v70
	v_cvt_f32_ubyte0_e32 v70, v71
	v_mul_f32_e32 v78, 0x3b808081, v70
	v_cvt_f32_ubyte1_e32 v70, v71
	v_mul_f32_e32 v79, 0x3b808081, v70
	v_cvt_f32_ubyte2_e32 v70, v71
	v_mul_f32_e32 v80, 0x3b808081, v70
	v_cvt_f32_ubyte3_e32 v70, v71
	v_mul_f32_e32 v76, 0x3b808081, v72
	v_mul_f32_e32 v81, 0x3b808081, v70
	s_waitcnt vmcnt(20)
; __device__ __forceinline__ unsigned cvt_pk_bf16(float lo, float hi) { unsigned r; asm volatile("v_cvt_pk_bf16_f32 %0, %1, %2" : "=v"(r) : "v"(lo), "v"(hi)); return r; }
; __device__ __forceinline__ float bf_lo(unsigned w) { return __uint_as_float(w << 16); }
; __device__ __forceinline__ float bf_hi(unsigned w) { return __uint_as_float(w & 0xffff0000u); }
;     __device__ __forceinline__ void operator()(const f32x4 (&acc)[2][2][4][2], const Unit& u, int wr, int wc, int fr, int fq) const {
;         const int row0 = u.pm * BM + wr * 64 + fr, col0 = u.pn * BM + wc * 32 + 8 * fq;
; #pragma unroll
;         for (int ai = 0; ai < 2; ++ai)
; #pragma unroll
;             for (int m = 0; m < 4; ++m) { const size_t row = (size_t)(row0 + ai * HALF + m * 16);
; #pragma unroll
;                 for (int bj = 0; bj < 2; ++bj) { const f32x4 v0 = acc[ai][bj][m][0], v1 = acc[ai][bj][m][1];
;                     const u32x2 g = *(const u32x2*)(G + row * ldg + col0 + bj * HALF);
;                     float o[8]; const float k255 = 1.0f / 255.0f;
;                     o[0] = v0[0] * ((float)(g.x & 0xffu) * k255); o[1] = v0[1] * ((float)((g.x >> 8) & 0xffu) * k255); o[2] = v0[2] * ((float)((g.x >> 16) & 0xffu) * k255); o[3] = v0[3] * ((float)(g.x >> 24) * k255);
;                     o[4] = v1[0] * ((float)(g.y & 0xffu) * k255); o[5] = v1[1] * ((float)((g.y >> 8) & 0xffu) * k255); o[6] = v1[2] * ((float)((g.y >> 16) & 0xffu) * k255); o[7] = v1[3] * ((float)(g.y >> 24) * k255);
;                     bf16_t* dst = MG + row * 1024 + col0 + bj * HALF;
;                     if (SECOND) { const u32x4 p = *(const u32x4*)dst;
;                         o[0] += bf_lo(p.x); o[1] += bf_hi(p.x); o[2] += bf_lo(p.y); o[3] += bf_hi(p.y); o[4] += bf_lo(p.z); o[5] += bf_hi(p.z); o[6] += bf_lo(p.w); o[7] += bf_hi(p.w); }
;                     u32x4 w; w.x = cvt_pk_bf16(o[0], o[1]); w.y = cvt_pk_bf16(o[2], o[3]); w.z = cvt_pk_bf16(o[4], o[5]); w.w = cvt_pk_bf16(o[6], o[7]);
;                     *(u32x4*)dst = w; } }
	s_nop 1
	v_mov_b32_e32 v70, v202
	v_mov_b32_e32 v71, v203
	v_mov_b32_e32 v72, v204
	v_mov_b32_e32 v73, v205
	v_lshlrev_b32_e32 v86, 16, v70
	v_fmac_f32_e32 v86, v62, v74
	v_and_b32_e32 v62, 0xffff0000, v70
	v_fmac_f32_e32 v62, v63, v75
	v_lshlrev_b32_e32 v63, 16, v71
	v_fmac_f32_e32 v63, v64, v76
	v_and_b32_e32 v64, 0xffff0000, v71
	v_fmac_f32_e32 v64, v65, v77
	v_lshlrev_b32_e32 v65, 16, v72
	v_and_b32_e32 v70, 0xffff0000, v72
	v_lshlrev_b32_e32 v71, 16, v73
	v_and_b32_e32 v72, 0xffff0000, v73
	v_fmac_f32_e32 v65, v58, v78
	v_fmac_f32_e32 v70, v59, v79
	v_fmac_f32_e32 v71, v60, v80
	v_fmac_f32_e32 v72, v61, v81
	v_cvt_pk_bf16_f32 v58, v86, v62
	v_cvt_pk_bf16_f32 v59, v63, v64
	v_cvt_pk_bf16_f32 v60, v65, v70
	v_cvt_pk_bf16_f32 v61, v71, v72
	global_store_dwordx4 v[68:69], v[58:61], off
	s_waitcnt vmcnt(22)
	s_nop 1
	v_mov_b32_e32 v58, v206
	v_mov_b32_e32 v59, v207
	v_cvt_f32_ubyte0_e32 v60, v58
	v_mul_f32_e32 v62, 0x3b808081, v60
	v_cvt_f32_ubyte1_e32 v60, v58
	v_mul_f32_e32 v63, 0x3b808081, v60
	v_cvt_f32_ubyte2_e32 v60, v58
	v_cvt_f32_ubyte3_e32 v58, v58
	v_mul_f32_e32 v65, 0x3b808081, v58
	v_cvt_f32_ubyte0_e32 v58, v59
	v_mul_f32_e32 v66, 0x3b808081, v58
	v_cvt_f32_ubyte1_e32 v58, v59
	v_mul_f32_e32 v67, 0x3b808081, v58
	v_cvt_f32_ubyte2_e32 v58, v59
	v_mul_f32_e32 v70, 0x3b808081, v58
	v_cvt_f32_ubyte3_e32 v58, v59
	v_mul_f32_e32 v64, 0x3b808081, v60
	v_mul_f32_e32 v71, 0x3b808081, v58
	s_waitcnt vmcnt(20)
	s_nop 1
	v_mov_b32_e32 v58, v208
	v_mov_b32_e32 v59, v209
	v_mov_b32_e32 v60, v210
	v_mov_b32_e32 v61, v211
	v_lshlrev_b32_e32 v72, 16, v58
	v_fmac_f32_e32 v72, v54, v62
	v_and_b32_e32 v54, 0xffff0000, v58
	v_fmac_f32_e32 v54, v55, v63
	v_lshlrev_b32_e32 v55, 16, v59
	v_fmac_f32_e32 v55, v56, v64
	v_and_b32_e32 v56, 0xffff0000, v59
	v_fmac_f32_e32 v56, v57, v65
	v_lshlrev_b32_e32 v57, 16, v60
	v_and_b32_e32 v58, 0xffff0000, v60
	v_lshlrev_b32_e32 v59, 16, v61
	v_and_b32_e32 v60, 0xffff0000, v61
	v_fmac_f32_e32 v57, v50, v66
	v_fmac_f32_e32 v58, v51, v67
	v_fmac_f32_e32 v59, v52, v70
	v_fmac_f32_e32 v60, v53, v71
	v_cvt_pk_bf16_f32 v50, v72, v54
	v_cvt_pk_bf16_f32 v51, v55, v56
	v_cvt_pk_bf16_f32 v52, v57, v58
	v_cvt_pk_bf16_f32 v53, v59, v60
	global_store_dwordx4 v[68:69], v[50:53], off offset:256
	s_nop 1
	v_lshl_add_u64 v[52:53], v[150:151], 0, s[26:27]
	v_lshl_add_u64 v[50:51], s[12:13], 0, v[52:53]
	v_lshl_add_u64 v[50:51], v[50:51], 0, v[148:149]
	v_lshl_add_u64 v[52:53], s[6:7], 0, v[52:53]
	v_lshl_add_u64 v[52:53], v[52:53], 0, v[146:147]
	s_mov_b64 s[26:27], 0x50000
	s_waitcnt vmcnt(18)
	s_nop 1
	v_mov_b32_e32 v54, v212
	v_mov_b32_e32 v55, v213
	v_cvt_f32_ubyte0_e32 v56, v54
	v_mul_f32_e32 v58, 0x3b808081, v56
	v_cvt_f32_ubyte1_e32 v56, v54
	v_mul_f32_e32 v59, 0x3b808081, v56
	v_cvt_f32_ubyte2_e32 v56, v54
	v_cvt_f32_ubyte3_e32 v54, v54
	v_mul_f32_e32 v61, 0x3b808081, v54
	v_cvt_f32_ubyte0_e32 v54, v55
	v_mul_f32_e32 v62, 0x3b808081, v54
	v_cvt_f32_ubyte1_e32 v54, v55
	v_mul_f32_e32 v63, 0x3b808081, v54
	v_cvt_f32_ubyte2_e32 v54, v55
	v_mul_f32_e32 v64, 0x3b808081, v54
	v_cvt_f32_ubyte3_e32 v54, v55
	v_mul_f32_e32 v60, 0x3b808081, v56
	v_mul_f32_e32 v65, 0x3b808081, v54
	s_waitcnt vmcnt(16)
	s_nop 1
	v_mov_b32_e32 v54, v214
	v_mov_b32_e32 v55, v215
	v_mov_b32_e32 v56, v216
	v_mov_b32_e32 v57, v217
	v_lshlrev_b32_e32 v66, 16, v54
	v_fmac_f32_e32 v66, v46, v58
	v_and_b32_e32 v46, 0xffff0000, v54
	v_fmac_f32_e32 v46, v47, v59
	v_lshlrev_b32_e32 v47, 16, v55
	v_fmac_f32_e32 v47, v48, v60
	v_and_b32_e32 v48, 0xffff0000, v55
	v_fmac_f32_e32 v48, v49, v61
	v_lshlrev_b32_e32 v49, 16, v56
	v_and_b32_e32 v54, 0xffff0000, v56
	v_lshlrev_b32_e32 v55, 16, v57
	v_and_b32_e32 v56, 0xffff0000, v57
	v_fmac_f32_e32 v49, v42, v62
	v_fmac_f32_e32 v54, v43, v63
	v_fmac_f32_e32 v55, v44, v64
	v_fmac_f32_e32 v56, v45, v65
	v_cvt_pk_bf16_f32 v42, v66, v46
	v_cvt_pk_bf16_f32 v43, v47, v48
	v_cvt_pk_bf16_f32 v44, v49, v54
	v_cvt_pk_bf16_f32 v45, v55, v56
	global_store_dwordx4 v[52:53], v[42:45], off
	s_waitcnt vmcnt(18)
	s_nop 1
	v_mov_b32_e32 v42, v218
	v_mov_b32_e32 v43, v219
	v_cvt_f32_ubyte0_e32 v44, v42
	v_mul_f32_e32 v46, 0x3b808081, v44
	v_cvt_f32_ubyte1_e32 v44, v42
	v_mul_f32_e32 v47, 0x3b808081, v44
	v_cvt_f32_ubyte2_e32 v44, v42
	v_cvt_f32_ubyte3_e32 v42, v42
	v_mul_f32_e32 v49, 0x3b808081, v42
	v_cvt_f32_ubyte0_e32 v42, v43
	v_mul_f32_e32 v50, 0x3b808081, v42
	v_cvt_f32_ubyte1_e32 v42, v43
	v_mul_f32_e32 v51, 0x3b808081, v42
	v_cvt_f32_ubyte2_e32 v42, v43
	v_mul_f32_e32 v54, 0x3b808081, v42
	v_cvt_f32_ubyte3_e32 v42, v43
	v_mul_f32_e32 v48, 0x3b808081, v44
	v_mul_f32_e32 v55, 0x3b808081, v42
	s_waitcnt vmcnt(16)
	s_nop 1
	v_mov_b32_e32 v42, v220
	v_mov_b32_e32 v43, v221
	v_mov_b32_e32 v44, v222
	v_mov_b32_e32 v45, v223
	v_lshlrev_b32_e32 v56, 16, v42
	v_fmac_f32_e32 v56, v38, v46
	v_and_b32_e32 v38, 0xffff0000, v42
	v_fmac_f32_e32 v38, v39, v47
	v_lshlrev_b32_e32 v39, 16, v43
	v_fmac_f32_e32 v39, v40, v48
	v_and_b32_e32 v40, 0xffff0000, v43
	v_fmac_f32_e32 v40, v41, v49
	v_lshlrev_b32_e32 v41, 16, v44
	v_and_b32_e32 v42, 0xffff0000, v44
	v_lshlrev_b32_e32 v43, 16, v45
	v_and_b32_e32 v44, 0xffff0000, v45
	v_fmac_f32_e32 v41, v34, v50
	v_fmac_f32_e32 v42, v35, v51
	v_fmac_f32_e32 v43, v36, v54
	v_fmac_f32_e32 v44, v37, v55
	v_cvt_pk_bf16_f32 v34, v56, v38
	v_cvt_pk_bf16_f32 v35, v39, v40
	v_cvt_pk_bf16_f32 v36, v41, v42
	v_cvt_pk_bf16_f32 v37, v43, v44
	global_store_dwordx4 v[52:53], v[34:37], off offset:256
	s_nop 1
	v_lshl_add_u64 v[36:37], v[150:151], 0, s[26:27]
	v_lshl_add_u64 v[34:35], s[12:13], 0, v[36:37]
	v_lshl_add_u64 v[34:35], v[34:35], 0, v[148:149]
	v_lshl_add_u64 v[36:37], s[6:7], 0, v[36:37]
	v_lshl_add_u64 v[36:37], v[36:37], 0, v[146:147]
	s_mov_b64 s[26:27], 0x58000
	s_waitcnt vmcnt(14)
; __device__ __forceinline__ unsigned cvt_pk_bf16(float lo, float hi) { unsigned r; asm volatile("v_cvt_pk_bf16_f32 %0, %1, %2" : "=v"(r) : "v"(lo), "v"(hi)); return r; }
; __device__ __forceinline__ float bf_lo(unsigned w) { return __uint_as_float(w << 16); }
; __device__ __forceinline__ float bf_hi(unsigned w) { return __uint_as_float(w & 0xffff0000u); }
;     __device__ __forceinline__ void operator()(const f32x4 (&acc)[2][2][4][2], const Unit& u, int wr, int wc, int fr, int fq) const {
;         const int row0 = u.pm * BM + wr * 64 + fr, col0 = u.pn * BM + wc * 32 + 8 * fq;
; #pragma unroll
;         for (int ai = 0; ai < 2; ++ai)
; #pragma unroll
;             for (int m = 0; m < 4; ++m) { const size_t row = (size_t)(row0 + ai * HALF + m * 16);
; #pragma unroll
;                 for (int bj = 0; bj < 2; ++bj) { const f32x4 v0 = acc[ai][bj][m][0], v1 = acc[ai][bj][m][1];
;                     const u32x2 g = *(const u32x2*)(G + row * ldg + col0 + bj * HALF);
;                     float o[8]; const float k255 = 1.0f / 255.0f;
;                     o[0] = v0[0] * ((float)(g.x & 0xffu) * k255); o[1] = v0[1] * ((float)((g.x >> 8) & 0xffu) * k255); o[2] = v0[2] * ((float)((g.x >> 16) & 0xffu) * k255); o[3] = v0[3] * ((float)(g.x >> 24) * k255);
;                     o[4] = v1[0] * ((float)(g.y & 0xffu) * k255); o[5] = v1[1] * ((float)((g.y >> 8) & 0xffu) * k255); o[6] = v1[2] * ((float)((g.y >> 16) & 0xffu) * k255); o[7] = v1[3] * ((float)(g.y >> 24) * k255);
;                     bf16_t* dst = MG + row * 1024 + col0 + bj * HALF;
;                     if (SECOND) { const u32x4 p = *(const u32x4*)dst;
;                         o[0] += bf_lo(p.x); o[1] += bf_hi(p.x); o[2] += bf_lo(p.y); o[3] += bf_hi(p.y); o[4] += bf_lo(p.z); o[5] += bf_hi(p.z); o[6] += bf_lo(p.w); o[7] += bf_hi(p.w); }
;                     u32x4 w; w.x = cvt_pk_bf16(o[0], o[1]); w.y = cvt_pk_bf16(o[2], o[3]); w.z = cvt_pk_bf16(o[4], o[5]); w.w = cvt_pk_bf16(o[6], o[7]);
;                     *(u32x4*)dst = w; } }
	s_nop 1
	v_mov_b32_e32 v38, v224
	v_mov_b32_e32 v39, v225
	v_cvt_f32_ubyte0_e32 v40, v38
	v_mul_f32_e32 v42, 0x3b808081, v40
	v_cvt_f32_ubyte1_e32 v40, v38
	v_mul_f32_e32 v43, 0x3b808081, v40
	v_cvt_f32_ubyte2_e32 v40, v38
	v_cvt_f32_ubyte3_e32 v38, v38
	v_mul_f32_e32 v45, 0x3b808081, v38
	v_cvt_f32_ubyte0_e32 v38, v39
	v_mul_f32_e32 v46, 0x3b808081, v38
	v_cvt_f32_ubyte1_e32 v38, v39
	v_mul_f32_e32 v47, 0x3b808081, v38
	v_cvt_f32_ubyte2_e32 v38, v39
	v_mul_f32_e32 v48, 0x3b808081, v38
	v_cvt_f32_ubyte3_e32 v38, v39
	v_mul_f32_e32 v44, 0x3b808081, v40
	v_mul_f32_e32 v49, 0x3b808081, v38
	s_waitcnt vmcnt(12)
	s_nop 1
	v_mov_b32_e32 v38, v226
	v_mov_b32_e32 v39, v227
	v_mov_b32_e32 v40, v228
	v_mov_b32_e32 v41, v229
	v_lshlrev_b32_e32 v50, 16, v38
	v_fmac_f32_e32 v50, v30, v42
	v_and_b32_e32 v30, 0xffff0000, v38
	v_fmac_f32_e32 v30, v31, v43
	v_lshlrev_b32_e32 v31, 16, v39
	v_fmac_f32_e32 v31, v32, v44
	v_and_b32_e32 v32, 0xffff0000, v39
	v_fmac_f32_e32 v32, v33, v45
	v_lshlrev_b32_e32 v33, 16, v40
	v_and_b32_e32 v38, 0xffff0000, v40
	v_lshlrev_b32_e32 v39, 16, v41
	v_and_b32_e32 v40, 0xffff0000, v41
	v_fmac_f32_e32 v33, v26, v46
	v_fmac_f32_e32 v38, v27, v47
	v_fmac_f32_e32 v39, v28, v48
	v_fmac_f32_e32 v40, v29, v49
	v_cvt_pk_bf16_f32 v26, v50, v30
	v_cvt_pk_bf16_f32 v27, v31, v32
	v_cvt_pk_bf16_f32 v28, v33, v38
	v_cvt_pk_bf16_f32 v29, v39, v40
	global_store_dwordx4 v[36:37], v[26:29], off
	s_waitcnt vmcnt(14)
	s_nop 1
	v_mov_b32_e32 v26, v230
	v_mov_b32_e32 v27, v231
	v_cvt_f32_ubyte0_e32 v28, v26
	v_mul_f32_e32 v30, 0x3b808081, v28
	v_cvt_f32_ubyte1_e32 v28, v26
	v_mul_f32_e32 v31, 0x3b808081, v28
	v_cvt_f32_ubyte2_e32 v28, v26
	v_cvt_f32_ubyte3_e32 v26, v26
	v_mul_f32_e32 v33, 0x3b808081, v26
	v_cvt_f32_ubyte0_e32 v26, v27
	v_mul_f32_e32 v34, 0x3b808081, v26
	v_cvt_f32_ubyte1_e32 v26, v27
	v_mul_f32_e32 v35, 0x3b808081, v26
	v_cvt_f32_ubyte2_e32 v26, v27
	v_mul_f32_e32 v38, 0x3b808081, v26
	v_cvt_f32_ubyte3_e32 v26, v27
	v_mul_f32_e32 v32, 0x3b808081, v28
	v_mul_f32_e32 v39, 0x3b808081, v26
	s_waitcnt vmcnt(12)
	s_nop 1
	v_mov_b32_e32 v26, v232
	v_mov_b32_e32 v27, v233
	v_mov_b32_e32 v28, v234
	v_mov_b32_e32 v29, v235
	v_lshlrev_b32_e32 v40, 16, v26
	v_fmac_f32_e32 v40, v22, v30
	v_and_b32_e32 v22, 0xffff0000, v26
	v_fmac_f32_e32 v22, v23, v31
	v_lshlrev_b32_e32 v23, 16, v27
	v_fmac_f32_e32 v23, v24, v32
	v_and_b32_e32 v24, 0xffff0000, v27
	v_fmac_f32_e32 v24, v25, v33
	v_lshlrev_b32_e32 v25, 16, v28
	v_and_b32_e32 v26, 0xffff0000, v28
	v_lshlrev_b32_e32 v27, 16, v29
	v_and_b32_e32 v28, 0xffff0000, v29
	v_fmac_f32_e32 v25, v18, v34
	v_fmac_f32_e32 v26, v19, v35
	v_fmac_f32_e32 v27, v20, v38
	v_fmac_f32_e32 v28, v21, v39
	v_cvt_pk_bf16_f32 v18, v40, v22
	v_cvt_pk_bf16_f32 v19, v23, v24
	v_cvt_pk_bf16_f32 v20, v25, v26
	v_cvt_pk_bf16_f32 v21, v27, v28
	global_store_dwordx4 v[36:37], v[18:21], off offset:256
	s_nop 1
	v_lshl_add_u64 v[20:21], v[150:151], 0, s[26:27]
	v_lshl_add_u64 v[18:19], s[12:13], 0, v[20:21]
	v_lshl_add_u64 v[18:19], v[18:19], 0, v[148:149]
	v_lshl_add_u64 v[20:21], s[6:7], 0, v[20:21]
	v_lshl_add_u64 v[20:21], v[20:21], 0, v[146:147]
	s_mov_b64 s[26:27], -1
	s_waitcnt vmcnt(10)
	s_nop 1
	v_mov_b32_e32 v22, v236
	v_mov_b32_e32 v23, v237
	v_cvt_f32_ubyte0_e32 v24, v22
	v_mul_f32_e32 v26, 0x3b808081, v24
	v_cvt_f32_ubyte1_e32 v24, v22
	v_mul_f32_e32 v27, 0x3b808081, v24
	v_cvt_f32_ubyte2_e32 v24, v22
	v_cvt_f32_ubyte3_e32 v22, v22
	v_mul_f32_e32 v29, 0x3b808081, v22
	v_cvt_f32_ubyte0_e32 v22, v23
	v_mul_f32_e32 v30, 0x3b808081, v22
	v_cvt_f32_ubyte1_e32 v22, v23
	v_mul_f32_e32 v31, 0x3b808081, v22
	v_cvt_f32_ubyte2_e32 v22, v23
	v_mul_f32_e32 v32, 0x3b808081, v22
	v_cvt_f32_ubyte3_e32 v22, v23
	v_mul_f32_e32 v28, 0x3b808081, v24
	v_mul_f32_e32 v33, 0x3b808081, v22
	s_waitcnt vmcnt(8)
	s_nop 1
	v_mov_b32_e32 v22, v238
	v_mov_b32_e32 v23, v239
	v_mov_b32_e32 v24, v240
	v_mov_b32_e32 v25, v241
	v_lshlrev_b32_e32 v34, 16, v22
	v_fmac_f32_e32 v34, v14, v26
	v_and_b32_e32 v14, 0xffff0000, v22
	v_fmac_f32_e32 v14, v15, v27
	v_lshlrev_b32_e32 v15, 16, v23
	v_fmac_f32_e32 v15, v16, v28
	v_and_b32_e32 v16, 0xffff0000, v23
	v_fmac_f32_e32 v16, v17, v29
	v_lshlrev_b32_e32 v17, 16, v24
	v_and_b32_e32 v22, 0xffff0000, v24
	v_lshlrev_b32_e32 v23, 16, v25
	v_and_b32_e32 v24, 0xffff0000, v25
	v_fmac_f32_e32 v17, v10, v30
	v_fmac_f32_e32 v22, v11, v31
	v_fmac_f32_e32 v23, v12, v32
	v_fmac_f32_e32 v24, v13, v33
	v_cvt_pk_bf16_f32 v10, v34, v14
	v_cvt_pk_bf16_f32 v11, v15, v16
	v_cvt_pk_bf16_f32 v12, v17, v22
	v_cvt_pk_bf16_f32 v13, v23, v24
	global_store_dwordx4 v[20:21], v[10:13], off
	s_waitcnt vmcnt(10)
	s_nop 1
	v_mov_b32_e32 v10, v242
	v_mov_b32_e32 v11, v243
	v_cvt_f32_ubyte0_e32 v12, v10
	v_mul_f32_e32 v14, 0x3b808081, v12
	v_cvt_f32_ubyte1_e32 v12, v10
	v_mul_f32_e32 v15, 0x3b808081, v12
	v_cvt_f32_ubyte2_e32 v12, v10
	v_cvt_f32_ubyte3_e32 v10, v10
	v_mul_f32_e32 v17, 0x3b808081, v10
	v_cvt_f32_ubyte0_e32 v10, v11
	v_mul_f32_e32 v18, 0x3b808081, v10
	v_cvt_f32_ubyte1_e32 v10, v11
	v_mul_f32_e32 v19, 0x3b808081, v10
	v_cvt_f32_ubyte2_e32 v10, v11
	v_mul_f32_e32 v22, 0x3b808081, v10
	v_cvt_f32_ubyte3_e32 v10, v11
	v_mul_f32_e32 v16, 0x3b808081, v12
	v_mul_f32_e32 v23, 0x3b808081, v10
	s_waitcnt vmcnt(8)
	s_nop 1
	v_mov_b32_e32 v10, v244
	v_mov_b32_e32 v11, v245
	v_mov_b32_e32 v12, v246
	v_mov_b32_e32 v13, v247
	v_lshlrev_b32_e32 v24, 16, v10
	v_fmac_f32_e32 v24, v6, v14
	v_and_b32_e32 v6, 0xffff0000, v10
	v_fmac_f32_e32 v6, v7, v15
	v_lshlrev_b32_e32 v7, 16, v11
	v_fmac_f32_e32 v7, v8, v16
	v_and_b32_e32 v8, 0xffff0000, v11
	v_fmac_f32_e32 v8, v9, v17
	v_lshlrev_b32_e32 v9, 16, v12
	v_and_b32_e32 v10, 0xffff0000, v12
	v_lshlrev_b32_e32 v11, 16, v13
	v_and_b32_e32 v12, 0xffff0000, v13
	v_fmac_f32_e32 v9, v2, v18
	v_fmac_f32_e32 v10, v3, v19
	v_fmac_f32_e32 v11, v4, v22
	v_fmac_f32_e32 v12, v5, v23
	v_cvt_pk_bf16_f32 v2, v24, v6
	v_cvt_pk_bf16_f32 v3, v7, v8
	v_cvt_pk_bf16_f32 v4, v9, v10
	v_cvt_pk_bf16_f32 v5, v11, v12
	global_store_dwordx4 v[20:21], v[2:5], off offset:256
	s_cbranch_vccnz .LBB0_696
	s_andn2_b64 vcc, exec, s[10:11]
	s_cbranch_vccnz .LBB0_695
	s_barrier
	s_branch .LBB0_695

; __device__ __forceinline__ float bf_lo(unsigned w) { return __uint_as_float(w << 16); }
; __device__ __forceinline__ float bf_hi(unsigned w) { return __uint_as_float(w & 0xffff0000u); }
;     __device__ __forceinline__ void operator()(const f32x4 (&acc)[2][2][4][2], const Unit& u, int wr, int wc, int fr, int fq) const {
;         const int row0 = u.pm * BM + wr * 64 + fr, col0 = u.pn * BM + wc * 32 + 4 * fq;
; #pragma unroll
;         for (int ai = 0; ai < 2; ++ai)
; #pragma unroll
;             for (int m = 0; m < 4; ++m) { const int lrow = row0 + ai * HALF + m * 16; float* orow = OUT + (size_t)(grow0 + lrow) * 1024; const bf16_t* brow = XB + (size_t)lrow * 1024;
; #pragma unroll
;                 for (int bj = 0; bj < 2; ++bj)
; #pragma unroll
;                     for (int n = 0; n < 2; ++n) { const int c = col0 + bj * HALF + n * 16; const u32x2 xw = *(const u32x2*)(brow + c);
;                         const f32x4 xv = (f32x4){bf_lo(xw.x), bf_hi(xw.x), bf_lo(xw.y), bf_hi(xw.y)}; *(f32x4*)(orow + c) = xv + acc[ai][bj][m][n]; } }
.LBB0_1038:
	v_lshl_add_u32 v144, s60, 8, v1
	v_lshl_or_b32 v142, s56, 8, v149
	v_ashrrev_i32_e32 v145, 31, v144
	v_lshlrev_b64 v[146:147], 11, v[144:145]
	v_ashrrev_i32_e32 v143, 31, v142
	v_lshl_add_u64 v[152:153], s[14:15], 0, v[146:147]
	v_lshlrev_b64 v[146:147], 1, v[142:143]
	v_lshl_add_u64 v[152:153], v[152:153], 0, v[146:147]
	v_mov_b32_e32 v252, v152
	v_mov_b32_e32 v253, v153
	s_mov_b32 s77, 0
	global_load_dwordx2 v[200:201], v[252:253], off nt
	global_load_dwordx2 v[202:203], v[252:253], off offset:32 nt
	global_load_dwordx2 v[204:205], v[252:253], off offset:256 nt
	global_load_dwordx2 v[206:207], v[252:253], off offset:288 nt
	s_mov_b32 s76, 0x8000
	v_lshl_add_u64 v[250:251], v[252:253], 0, s[76:77]
	global_load_dwordx2 v[208:209], v[250:251], off nt
	global_load_dwordx2 v[210:211], v[250:251], off offset:32 nt
	global_load_dwordx2 v[212:213], v[250:251], off offset:256 nt
	global_load_dwordx2 v[214:215], v[250:251], off offset:288 nt
	s_mov_b32 s76, 0x10000
	v_lshl_add_u64 v[250:251], v[252:253], 0, s[76:77]
	global_load_dwordx2 v[216:217], v[250:251], off nt
	global_load_dwordx2 v[218:219], v[250:251], off offset:32 nt
	global_load_dwordx2 v[220:221], v[250:251], off offset:256 nt
	global_load_dwordx2 v[222:223], v[250:251], off offset:288 nt
	s_mov_b32 s76, 0x18000
	v_lshl_add_u64 v[250:251], v[252:253], 0, s[76:77]
	global_load_dwordx2 v[224:225], v[250:251], off nt
	global_load_dwordx2 v[226:227], v[250:251], off offset:32 nt
	global_load_dwordx2 v[228:229], v[250:251], off offset:256 nt
	global_load_dwordx2 v[230:231], v[250:251], off offset:288 nt
	s_mov_b32 s76, 0x40000
	v_lshl_add_u64 v[250:251], v[252:253], 0, s[76:77]
	global_load_dwordx2 v[232:233], v[250:251], off nt
	global_load_dwordx2 v[234:235], v[250:251], off offset:32 nt
	global_load_dwordx2 v[236:237], v[250:251], off offset:256 nt
	global_load_dwordx2 v[238:239], v[250:251], off offset:288 nt
	s_mov_b32 s76, 0x48000
	v_lshl_add_u64 v[250:251], v[252:253], 0, s[76:77]
	global_load_dwordx2 v[240:241], v[250:251], off nt
	global_load_dwordx2 v[242:243], v[250:251], off offset:32 nt
	global_load_dwordx2 v[244:245], v[250:251], off offset:256 nt
	global_load_dwordx2 v[246:247], v[250:251], off offset:288 nt
	v_add_u32_e32 v156, s48, v144
	v_ashrrev_i32_e32 v157, 31, v156
	v_lshlrev_b64 v[156:157], 12, v[156:157]
	v_lshlrev_b64 v[142:143], 2, v[142:143]
	v_lshl_add_u64 v[156:157], s[8:9], 0, v[156:157]
	v_lshl_add_u64 v[156:157], v[156:157], 0, v[142:143]
	s_and_b64 vcc, exec, s[4:5]
	s_mov_b64 s[4:5], -1
	s_waitcnt vmcnt(23)
	s_nop 1
	v_mov_b32_e32 v154, v200
	v_mov_b32_e32 v155, v201
	v_lshlrev_b32_e32 v158, 16, v154
	v_and_b32_e32 v159, 0xffff0000, v154
	v_lshlrev_b32_e32 v154, 16, v155
	v_and_b32_e32 v155, 0xffff0000, v155
	v_pk_add_f32 v[132:133], v[132:133], v[154:155]
	v_pk_add_f32 v[130:131], v[130:131], v[158:159]
	global_store_dwordx4 v[156:157], v[130:133], off
	s_waitcnt vmcnt(23)
	s_nop 1
	v_mov_b32_e32 v130, v202
	v_mov_b32_e32 v131, v203
	v_lshlrev_b32_e32 v132, 16, v130
	v_and_b32_e32 v133, 0xffff0000, v130
	v_lshlrev_b32_e32 v130, 16, v131
	v_and_b32_e32 v131, 0xffff0000, v131
	v_pk_add_f32 v[128:129], v[128:129], v[130:131]
	v_pk_add_f32 v[126:127], v[126:127], v[132:133]
	global_store_dwordx4 v[156:157], v[126:129], off offset:64
	s_waitcnt vmcnt(23)
	s_nop 1
	v_mov_b32_e32 v126, v204
	v_mov_b32_e32 v127, v205
	v_lshlrev_b32_e32 v128, 16, v126
	v_and_b32_e32 v129, 0xffff0000, v126
	v_lshlrev_b32_e32 v126, 16, v127
	v_and_b32_e32 v127, 0xffff0000, v127
	v_pk_add_f32 v[124:125], v[124:125], v[126:127]
	v_pk_add_f32 v[122:123], v[122:123], v[128:129]
	global_store_dwordx4 v[156:157], v[122:125], off offset:512
	s_waitcnt vmcnt(23)
	s_nop 1
	v_mov_b32_e32 v122, v206
	v_mov_b32_e32 v123, v207
	s_mov_b32 s76, 0x50000
	v_lshl_add_u64 v[250:251], v[252:253], 0, s[76:77]
	global_load_dwordx2 v[200:201], v[250:251], off nt
	global_load_dwordx2 v[202:203], v[250:251], off offset:32 nt
	global_load_dwordx2 v[204:205], v[250:251], off offset:256 nt
	global_load_dwordx2 v[206:207], v[250:251], off offset:288 nt
	v_lshlrev_b32_e32 v128, 16, v122
	v_or_b32_e32 v124, 16, v144
	v_ashrrev_i32_e32 v125, 31, v124
	v_lshlrev_b64 v[126:127], 11, v[124:125]
	v_and_b32_e32 v129, 0xffff0000, v122
	v_lshlrev_b32_e32 v122, 16, v123
	v_and_b32_e32 v123, 0xffff0000, v123
	v_lshl_add_u64 v[126:127], s[14:15], 0, v[126:127]
	v_pk_add_f32 v[116:117], v[116:117], v[122:123]
	v_pk_add_f32 v[114:115], v[114:115], v[128:129]
	v_lshl_add_u64 v[126:127], v[126:127], 0, v[146:147]
	global_store_dwordx4 v[156:157], v[114:117], off offset:576
	s_waitcnt vmcnt(27)
	s_nop 1
	v_mov_b32_e32 v114, v208
	v_mov_b32_e32 v115, v209
	v_and_b32_e32 v125, 0xffff0000, v114
	v_add_u32_e32 v116, s48, v124
	v_ashrrev_i32_e32 v117, 31, v116
	v_lshlrev_b64 v[116:117], 12, v[116:117]
	v_lshl_add_u64 v[116:117], s[8:9], 0, v[116:117]
	v_lshlrev_b32_e32 v124, 16, v114
	v_lshlrev_b32_e32 v114, 16, v115
	v_and_b32_e32 v115, 0xffff0000, v115
	v_lshl_add_u64 v[122:123], v[116:117], 0, v[142:143]
	v_pk_add_f32 v[116:117], v[120:121], v[114:115]
	v_pk_add_f32 v[114:115], v[118:119], v[124:125]
	global_store_dwordx4 v[122:123], v[114:117], off
	s_waitcnt vmcnt(27)
	s_nop 1
	v_mov_b32_e32 v114, v210
	v_mov_b32_e32 v115, v211
	v_lshlrev_b32_e32 v116, 16, v114
	v_and_b32_e32 v117, 0xffff0000, v114
	v_lshlrev_b32_e32 v114, 16, v115
	v_and_b32_e32 v115, 0xffff0000, v115
	v_pk_add_f32 v[112:113], v[112:113], v[114:115]
	v_pk_add_f32 v[110:111], v[110:111], v[116:117]
	global_store_dwordx4 v[122:123], v[110:113], off offset:64
	s_waitcnt vmcnt(27)
; __device__ __forceinline__ float bf_lo(unsigned w) { return __uint_as_float(w << 16); }
; __device__ __forceinline__ float bf_hi(unsigned w) { return __uint_as_float(w & 0xffff0000u); }
;     __device__ __forceinline__ void operator()(const f32x4 (&acc)[2][2][4][2], const Unit& u, int wr, int wc, int fr, int fq) const {
;     ...
;             for (int m = 0; m < 4; ++m) { const int lrow = row0 + ai * HALF + m * 16; float* orow = OUT + (size_t)(grow0 + lrow) * 1024; const bf16_t* brow = XB + (size_t)lrow * 1024;
; #pragma unroll
;                 for (int bj = 0; bj < 2; ++bj)
; #pragma unroll
;                     for (int n = 0; n < 2; ++n) { const int c = col0 + bj * HALF + n * 16; const u32x2 xw = *(const u32x2*)(brow + c);
;                         const f32x4 xv = (f32x4){bf_lo(xw.x), bf_hi(xw.x), bf_lo(xw.y), bf_hi(xw.y)}; *(f32x4*)(orow + c) = xv + acc[ai][bj][m][n]; } }
	s_nop 1
	v_mov_b32_e32 v110, v212
	v_mov_b32_e32 v111, v213
	v_lshlrev_b32_e32 v112, 16, v110
	v_and_b32_e32 v113, 0xffff0000, v110
	v_lshlrev_b32_e32 v110, 16, v111
	v_and_b32_e32 v111, 0xffff0000, v111
	v_pk_add_f32 v[108:109], v[108:109], v[110:111]
	v_pk_add_f32 v[106:107], v[106:107], v[112:113]
	global_store_dwordx4 v[122:123], v[106:109], off offset:512
	s_waitcnt vmcnt(27)
	s_nop 1
	v_mov_b32_e32 v106, v214
	v_mov_b32_e32 v107, v215
	s_mov_b32 s76, 0x58000
	v_lshl_add_u64 v[250:251], v[252:253], 0, s[76:77]
	global_load_dwordx2 v[208:209], v[250:251], off nt
	global_load_dwordx2 v[210:211], v[250:251], off offset:32 nt
	global_load_dwordx2 v[212:213], v[250:251], off offset:256 nt
	global_load_dwordx2 v[214:215], v[250:251], off offset:288 nt
	v_lshlrev_b32_e32 v112, 16, v106
	v_or_b32_e32 v108, 32, v144
	v_ashrrev_i32_e32 v109, 31, v108
	v_lshlrev_b64 v[110:111], 11, v[108:109]
	v_and_b32_e32 v113, 0xffff0000, v106
	v_lshlrev_b32_e32 v106, 16, v107
	v_and_b32_e32 v107, 0xffff0000, v107
	v_lshl_add_u64 v[110:111], s[14:15], 0, v[110:111]
	v_pk_add_f32 v[100:101], v[100:101], v[106:107]
	v_pk_add_f32 v[98:99], v[98:99], v[112:113]
	v_lshl_add_u64 v[110:111], v[110:111], 0, v[146:147]
	global_store_dwordx4 v[122:123], v[98:101], off offset:576
	s_waitcnt vmcnt(31)
	s_nop 1
	v_mov_b32_e32 v98, v216
	v_mov_b32_e32 v99, v217
	v_and_b32_e32 v109, 0xffff0000, v98
	v_add_u32_e32 v100, s48, v108
	v_ashrrev_i32_e32 v101, 31, v100
	v_lshlrev_b64 v[100:101], 12, v[100:101]
	v_lshl_add_u64 v[100:101], s[8:9], 0, v[100:101]
	v_lshlrev_b32_e32 v108, 16, v98
	v_lshlrev_b32_e32 v98, 16, v99
	v_and_b32_e32 v99, 0xffff0000, v99
	v_lshl_add_u64 v[106:107], v[100:101], 0, v[142:143]
	v_pk_add_f32 v[100:101], v[104:105], v[98:99]
	v_pk_add_f32 v[98:99], v[102:103], v[108:109]
	global_store_dwordx4 v[106:107], v[98:101], off
	s_waitcnt vmcnt(31)
	s_nop 1
	v_mov_b32_e32 v98, v218
	v_mov_b32_e32 v99, v219
	v_lshlrev_b32_e32 v100, 16, v98
	v_and_b32_e32 v101, 0xffff0000, v98
	v_lshlrev_b32_e32 v98, 16, v99
	v_and_b32_e32 v99, 0xffff0000, v99
	v_pk_add_f32 v[96:97], v[96:97], v[98:99]
	v_pk_add_f32 v[94:95], v[94:95], v[100:101]
	global_store_dwordx4 v[106:107], v[94:97], off offset:64
	s_waitcnt vmcnt(31)
	s_nop 1
	v_mov_b32_e32 v94, v220
	v_mov_b32_e32 v95, v221
	v_lshlrev_b32_e32 v96, 16, v94
	v_and_b32_e32 v97, 0xffff0000, v94
	v_lshlrev_b32_e32 v94, 16, v95
	v_and_b32_e32 v95, 0xffff0000, v95
	v_pk_add_f32 v[92:93], v[92:93], v[94:95]
	v_pk_add_f32 v[90:91], v[90:91], v[96:97]
	global_store_dwordx4 v[106:107], v[90:93], off offset:512
	s_waitcnt vmcnt(31)
	s_nop 1
	v_mov_b32_e32 v90, v222
	v_mov_b32_e32 v91, v223
	v_lshlrev_b32_e32 v96, 16, v90
	v_or_b32_e32 v92, 48, v144
	v_ashrrev_i32_e32 v93, 31, v92
	v_lshlrev_b64 v[94:95], 11, v[92:93]
	v_and_b32_e32 v97, 0xffff0000, v90
	v_lshlrev_b32_e32 v90, 16, v91
	v_and_b32_e32 v91, 0xffff0000, v91
	v_lshl_add_u64 v[94:95], s[14:15], 0, v[94:95]
	v_pk_add_f32 v[80:81], v[80:81], v[90:91]
	v_pk_add_f32 v[78:79], v[78:79], v[96:97]
	v_lshl_add_u64 v[94:95], v[94:95], 0, v[146:147]
	global_store_dwordx4 v[106:107], v[78:81], off offset:576
	s_waitcnt vmcnt(31)
	s_nop 1
	v_mov_b32_e32 v78, v224
	v_mov_b32_e32 v79, v225
	v_and_b32_e32 v93, 0xffff0000, v78
	v_add_u32_e32 v80, s48, v92
	v_ashrrev_i32_e32 v81, 31, v80
	v_lshlrev_b64 v[80:81], 12, v[80:81]
	v_lshl_add_u64 v[80:81], s[8:9], 0, v[80:81]
	v_lshlrev_b32_e32 v92, 16, v78
	v_lshlrev_b32_e32 v78, 16, v79
	v_and_b32_e32 v79, 0xffff0000, v79
	v_lshl_add_u64 v[90:91], v[80:81], 0, v[142:143]
	v_pk_add_f32 v[80:81], v[88:89], v[78:79]
	v_pk_add_f32 v[78:79], v[86:87], v[92:93]
	global_store_dwordx4 v[90:91], v[78:81], off
	s_waitcnt vmcnt(31)
	s_nop 1
	v_mov_b32_e32 v78, v226
	v_mov_b32_e32 v79, v227
	v_lshlrev_b32_e32 v80, 16, v78
	v_and_b32_e32 v81, 0xffff0000, v78
	v_lshlrev_b32_e32 v78, 16, v79
	v_and_b32_e32 v79, 0xffff0000, v79
	v_pk_add_f32 v[76:77], v[76:77], v[78:79]
	v_pk_add_f32 v[74:75], v[74:75], v[80:81]
	global_store_dwordx4 v[90:91], v[74:77], off offset:64
	s_waitcnt vmcnt(31)
	s_nop 1
	v_mov_b32_e32 v74, v228
	v_mov_b32_e32 v75, v229
	v_lshlrev_b32_e32 v76, 16, v74
	v_and_b32_e32 v77, 0xffff0000, v74
	v_lshlrev_b32_e32 v74, 16, v75
	v_and_b32_e32 v75, 0xffff0000, v75
	v_pk_add_f32 v[72:73], v[72:73], v[74:75]
	v_pk_add_f32 v[70:71], v[70:71], v[76:77]
	global_store_dwordx4 v[90:91], v[70:73], off offset:512
	s_waitcnt vmcnt(31)
	s_nop 1
	v_mov_b32_e32 v70, v230
	v_mov_b32_e32 v71, v231
	v_lshlrev_b32_e32 v76, 16, v70
	v_add_u32_e32 v72, 0x80, v144
	v_ashrrev_i32_e32 v73, 31, v72
	v_lshlrev_b64 v[74:75], 11, v[72:73]
	v_and_b32_e32 v77, 0xffff0000, v70
	v_lshlrev_b32_e32 v70, 16, v71
	v_and_b32_e32 v71, 0xffff0000, v71
	v_lshl_add_u64 v[74:75], s[14:15], 0, v[74:75]
	v_pk_add_f32 v[68:69], v[68:69], v[70:71]
	v_pk_add_f32 v[66:67], v[66:67], v[76:77]
	v_lshl_add_u64 v[74:75], v[74:75], 0, v[146:147]
	global_store_dwordx4 v[90:91], v[66:69], off offset:576
	s_waitcnt vmcnt(31)
	s_nop 1
	v_mov_b32_e32 v66, v232
	v_mov_b32_e32 v67, v233
	v_lshlrev_b32_e32 v70, 16, v66
	v_add_u32_e32 v68, s48, v72
	v_ashrrev_i32_e32 v69, 31, v68
	v_lshlrev_b64 v[68:69], 12, v[68:69]
	v_lshl_add_u64 v[68:69], s[8:9], 0, v[68:69]
	v_and_b32_e32 v71, 0xffff0000, v66
	v_lshlrev_b32_e32 v66, 16, v67
	v_and_b32_e32 v67, 0xffff0000, v67
	v_lshl_add_u64 v[68:69], v[68:69], 0, v[142:143]
	v_pk_add_f32 v[64:65], v[64:65], v[66:67]
	v_pk_add_f32 v[62:63], v[62:63], v[70:71]
	global_store_dwordx4 v[68:69], v[62:65], off
	s_waitcnt vmcnt(31)
; __device__ __forceinline__ float bf_lo(unsigned w) { return __uint_as_float(w << 16); }
; __device__ __forceinline__ float bf_hi(unsigned w) { return __uint_as_float(w & 0xffff0000u); }
; #define PG8_BAR __builtin_amdgcn_s_barrier()
;     __device__ __forceinline__ void operator()(const f32x4 (&acc)[2][2][4][2], const Unit& u, int wr, int wc, int fr, int fq) const {
;     ...
;             for (int m = 0; m < 4; ++m) { const int lrow = row0 + ai * HALF + m * 16; float* orow = OUT + (size_t)(grow0 + lrow) * 1024; const bf16_t* brow = XB + (size_t)lrow * 1024;
; #pragma unroll
;                 for (int bj = 0; bj < 2; ++bj)
; #pragma unroll
;                     for (int n = 0; n < 2; ++n) { const int c = col0 + bj * HALF + n * 16; const u32x2 xw = *(const u32x2*)(brow + c);
;                         const f32x4 xv = (f32x4){bf_lo(xw.x), bf_hi(xw.x), bf_lo(xw.y), bf_hi(xw.y)}; *(f32x4*)(orow + c) = xv + acc[ai][bj][m][n]; } }
; template <class Epi, class Sched, bool ALIGN_EPI = false, bool SP2 = false>
; __device__ __forceinline__ void gemm_phase(PG8_LAS unsigned char* lds, const Gemm g, const Sched& S, const Epi& E) {
;     ...
;         if (!has_next) break;
; #pragma unroll
;         for (int a = 0; a < 2; ++a)
; #pragma unroll
;             for (int b = 0; b < 2; ++b)
; #pragma unroll
;                 for (int m = 0; m < 4; ++m)
; #pragma unroll
;                     for (int n = 0; n < 2; ++n) acc[a][b][m][n] = (f32x4){0.f, 0.f, 0.f, 0.f};
;         cur = nxt; cA = nA; cB = nB; ++ui;
;         if constexpr (ALIGN_EPI) { if (wr == 1) PG8_BAR; }
	s_nop 1
	v_mov_b32_e32 v62, v234
	v_mov_b32_e32 v63, v235
	v_lshlrev_b32_e32 v64, 16, v62
	v_and_b32_e32 v65, 0xffff0000, v62
	v_lshlrev_b32_e32 v62, 16, v63
	v_and_b32_e32 v63, 0xffff0000, v63
	v_pk_add_f32 v[60:61], v[60:61], v[62:63]
	v_pk_add_f32 v[58:59], v[58:59], v[64:65]
	global_store_dwordx4 v[68:69], v[58:61], off offset:64
	s_waitcnt vmcnt(31)
	s_nop 1
	v_mov_b32_e32 v58, v236
	v_mov_b32_e32 v59, v237
	v_lshlrev_b32_e32 v60, 16, v58
	v_and_b32_e32 v61, 0xffff0000, v58
	v_lshlrev_b32_e32 v58, 16, v59
	v_and_b32_e32 v59, 0xffff0000, v59
	v_pk_add_f32 v[56:57], v[56:57], v[58:59]
	v_pk_add_f32 v[54:55], v[54:55], v[60:61]
	global_store_dwordx4 v[68:69], v[54:57], off offset:512
	s_waitcnt vmcnt(31)
	s_nop 1
	v_mov_b32_e32 v54, v238
	v_mov_b32_e32 v55, v239
	v_lshlrev_b32_e32 v60, 16, v54
	v_add_u32_e32 v56, 0x90, v144
	v_ashrrev_i32_e32 v57, 31, v56
	v_lshlrev_b64 v[58:59], 11, v[56:57]
	v_and_b32_e32 v61, 0xffff0000, v54
	v_lshlrev_b32_e32 v54, 16, v55
	v_and_b32_e32 v55, 0xffff0000, v55
	v_lshl_add_u64 v[58:59], s[14:15], 0, v[58:59]
	v_pk_add_f32 v[48:49], v[48:49], v[54:55]
	v_pk_add_f32 v[46:47], v[46:47], v[60:61]
	v_lshl_add_u64 v[58:59], v[58:59], 0, v[146:147]
	global_store_dwordx4 v[68:69], v[46:49], off offset:576
	s_waitcnt vmcnt(31)
	s_nop 1
	v_mov_b32_e32 v46, v240
	v_mov_b32_e32 v47, v241
	v_and_b32_e32 v57, 0xffff0000, v46
	v_add_u32_e32 v48, s48, v56
	v_ashrrev_i32_e32 v49, 31, v48
	v_lshlrev_b64 v[48:49], 12, v[48:49]
	v_lshl_add_u64 v[48:49], s[8:9], 0, v[48:49]
	v_lshlrev_b32_e32 v56, 16, v46
	v_lshlrev_b32_e32 v46, 16, v47
	v_and_b32_e32 v47, 0xffff0000, v47
	v_lshl_add_u64 v[54:55], v[48:49], 0, v[142:143]
	v_pk_add_f32 v[48:49], v[52:53], v[46:47]
	v_pk_add_f32 v[46:47], v[50:51], v[56:57]
	global_store_dwordx4 v[54:55], v[46:49], off
	s_waitcnt vmcnt(31)
	s_nop 1
	v_mov_b32_e32 v46, v242
	v_mov_b32_e32 v47, v243
	v_lshlrev_b32_e32 v48, 16, v46
	v_and_b32_e32 v49, 0xffff0000, v46
	v_lshlrev_b32_e32 v46, 16, v47
	v_and_b32_e32 v47, 0xffff0000, v47
	v_pk_add_f32 v[44:45], v[44:45], v[46:47]
	v_pk_add_f32 v[42:43], v[42:43], v[48:49]
	global_store_dwordx4 v[54:55], v[42:45], off offset:64
	s_waitcnt vmcnt(31)
	s_nop 1
	v_mov_b32_e32 v42, v244
	v_mov_b32_e32 v43, v245
	v_lshlrev_b32_e32 v44, 16, v42
	v_and_b32_e32 v45, 0xffff0000, v42
	v_lshlrev_b32_e32 v42, 16, v43
	v_and_b32_e32 v43, 0xffff0000, v43
	v_pk_add_f32 v[40:41], v[40:41], v[42:43]
	v_pk_add_f32 v[38:39], v[38:39], v[44:45]
	global_store_dwordx4 v[54:55], v[38:41], off offset:512
	s_waitcnt vmcnt(31)
	s_nop 1
	v_mov_b32_e32 v38, v246
	v_mov_b32_e32 v39, v247
	v_lshlrev_b32_e32 v44, 16, v38
	v_add_u32_e32 v40, 0xa0, v144
	v_ashrrev_i32_e32 v41, 31, v40
	v_lshlrev_b64 v[42:43], 11, v[40:41]
	v_and_b32_e32 v45, 0xffff0000, v38
	v_lshlrev_b32_e32 v38, 16, v39
	v_and_b32_e32 v39, 0xffff0000, v39
	v_lshl_add_u64 v[42:43], s[14:15], 0, v[42:43]
	v_pk_add_f32 v[32:33], v[32:33], v[38:39]
	v_pk_add_f32 v[30:31], v[30:31], v[44:45]
	v_lshl_add_u64 v[42:43], v[42:43], 0, v[146:147]
	global_store_dwordx4 v[54:55], v[30:33], off offset:576
	s_waitcnt vmcnt(28)
	s_nop 1
	v_mov_b32_e32 v30, v200
	v_mov_b32_e32 v31, v201
	v_and_b32_e32 v41, 0xffff0000, v30
	v_add_u32_e32 v32, s48, v40
	v_ashrrev_i32_e32 v33, 31, v32
	v_lshlrev_b64 v[32:33], 12, v[32:33]
	v_lshl_add_u64 v[32:33], s[8:9], 0, v[32:33]
	v_lshlrev_b32_e32 v40, 16, v30
	v_lshlrev_b32_e32 v30, 16, v31
	v_and_b32_e32 v31, 0xffff0000, v31
	v_lshl_add_u64 v[38:39], v[32:33], 0, v[142:143]
	v_pk_add_f32 v[32:33], v[36:37], v[30:31]
	v_pk_add_f32 v[30:31], v[34:35], v[40:41]
	global_store_dwordx4 v[38:39], v[30:33], off
	s_waitcnt vmcnt(28)
	s_nop 1
	v_mov_b32_e32 v30, v202
	v_mov_b32_e32 v31, v203
	v_lshlrev_b32_e32 v32, 16, v30
	v_and_b32_e32 v33, 0xffff0000, v30
	v_lshlrev_b32_e32 v30, 16, v31
	v_and_b32_e32 v31, 0xffff0000, v31
	v_pk_add_f32 v[28:29], v[28:29], v[30:31]
	v_pk_add_f32 v[26:27], v[26:27], v[32:33]
	global_store_dwordx4 v[38:39], v[26:29], off offset:64
	s_waitcnt vmcnt(28)
	s_nop 1
	v_mov_b32_e32 v26, v204
	v_mov_b32_e32 v27, v205
	v_lshlrev_b32_e32 v28, 16, v26
	v_and_b32_e32 v29, 0xffff0000, v26
	v_lshlrev_b32_e32 v26, 16, v27
	v_and_b32_e32 v27, 0xffff0000, v27
	v_pk_add_f32 v[24:25], v[24:25], v[26:27]
	v_pk_add_f32 v[22:23], v[22:23], v[28:29]
	global_store_dwordx4 v[38:39], v[22:25], off offset:512
	s_waitcnt vmcnt(28)
	s_nop 1
	v_mov_b32_e32 v22, v206
	v_mov_b32_e32 v23, v207
	v_lshlrev_b32_e32 v28, 16, v22
	v_add_u32_e32 v24, 0xb0, v144
	v_ashrrev_i32_e32 v25, 31, v24
	v_lshlrev_b64 v[26:27], 11, v[24:25]
	v_and_b32_e32 v29, 0xffff0000, v22
	v_lshlrev_b32_e32 v22, 16, v23
	v_and_b32_e32 v23, 0xffff0000, v23
	v_lshl_add_u64 v[26:27], s[14:15], 0, v[26:27]
	v_pk_add_f32 v[16:17], v[16:17], v[22:23]
	v_pk_add_f32 v[14:15], v[14:15], v[28:29]
	v_lshl_add_u64 v[26:27], v[26:27], 0, v[146:147]
	global_store_dwordx4 v[38:39], v[14:17], off offset:576
	s_waitcnt vmcnt(24)
	s_nop 1
	v_mov_b32_e32 v14, v208
	v_mov_b32_e32 v15, v209
	v_and_b32_e32 v25, 0xffff0000, v14
	v_add_u32_e32 v16, s48, v24
	v_ashrrev_i32_e32 v17, 31, v16
	v_lshlrev_b64 v[16:17], 12, v[16:17]
	v_lshl_add_u64 v[16:17], s[8:9], 0, v[16:17]
	v_lshlrev_b32_e32 v24, 16, v14
	v_lshlrev_b32_e32 v14, 16, v15
	v_and_b32_e32 v15, 0xffff0000, v15
	v_lshl_add_u64 v[22:23], v[16:17], 0, v[142:143]
	v_pk_add_f32 v[16:17], v[20:21], v[14:15]
	v_pk_add_f32 v[14:15], v[18:19], v[24:25]
	global_store_dwordx4 v[22:23], v[14:17], off
	s_waitcnt vmcnt(24)
	s_nop 1
	v_mov_b32_e32 v14, v210
	v_mov_b32_e32 v15, v211
	v_lshlrev_b32_e32 v16, 16, v14
	v_and_b32_e32 v17, 0xffff0000, v14
	v_lshlrev_b32_e32 v14, 16, v15
	v_and_b32_e32 v15, 0xffff0000, v15
	v_pk_add_f32 v[12:13], v[12:13], v[14:15]
	v_pk_add_f32 v[10:11], v[10:11], v[16:17]
	global_store_dwordx4 v[22:23], v[10:13], off offset:64
	s_waitcnt vmcnt(24)
	s_nop 1
	v_mov_b32_e32 v10, v212
	v_mov_b32_e32 v11, v213
	v_lshlrev_b32_e32 v12, 16, v10
	v_and_b32_e32 v13, 0xffff0000, v10
	v_lshlrev_b32_e32 v10, 16, v11
	v_and_b32_e32 v11, 0xffff0000, v11
	v_pk_add_f32 v[8:9], v[8:9], v[10:11]
	v_pk_add_f32 v[6:7], v[6:7], v[12:13]
	global_store_dwordx4 v[22:23], v[6:9], off offset:512
	s_waitcnt vmcnt(24)
	s_nop 1
	v_mov_b32_e32 v6, v214
	v_mov_b32_e32 v7, v215
	v_lshlrev_b32_e32 v8, 16, v6
	v_and_b32_e32 v9, 0xffff0000, v6
	v_lshlrev_b32_e32 v6, 16, v7
	v_and_b32_e32 v7, 0xffff0000, v7
	v_pk_add_f32 v[4:5], v[4:5], v[6:7]
	v_pk_add_f32 v[2:3], v[2:3], v[8:9]
	global_store_dwordx4 v[22:23], v[2:5], off offset:576
	s_cbranch_vccnz .LBB0_1027
	s_andn2_b64 vcc, exec, s[10:11]
	s_cbranch_vccnz .LBB0_1026
	s_barrier
	s_branch .LBB0_1026
